# GEMM K-loops on 16x16x32 bf16 MFMA (in-place permlane swap to the 32x32 layout), barrier after the 7th A-block group, two LDS-DMA issues per group
# speedup vs baseline: 1.0166x; 1.0166x over previous
.Lg161_loop:
	s_add_u32 s51, s50, 0x10000
	s_sub_u32 s53, s51, 0x28000
	s_cmp_ge_u32 s51, 0x28000
	s_cselect_b32 s51, s53, s51
	s_add_u32 s52, s49, 0x20000
	s_sub_u32 s53, s52, 0x28000
	s_cmp_ge_u32 s52, 0x28000
	s_cselect_b32 s52, s53, s52
	v_add_u32_e32 v137, s50, v135
	s_waitcnt lgkmcnt(4)
	s_waitcnt lgkmcnt(3)
	v_mfma_f32_16x16x32_bf16 v[112:115], v[164:167], v[224:227], v[112:115]
	v_mfma_f32_16x16x32_bf16 v[120:123], v[168:171], v[224:227], v[120:123]
	v_mfma_f32_16x16x32_bf16 v[96:99], v[172:175], v[224:227], v[96:99]
	v_mfma_f32_16x16x32_bf16 v[104:107], v[176:179], v[224:227], v[104:107]
	s_add_u32 m0, s51, s48
	s_nop 0
	global_load_lds_dwordx4 v139, s[64:65]
	s_add_u32 s64, s64, 0x80
	s_addc_u32 s65, s65, 0
	s_add_u32 s53, s51, s48
	s_add_u32 m0, s53, 0x2000
	s_nop 0
	global_load_lds_dwordx4 v139, s[66:67]
	s_add_u32 s66, s66, 0x80
	s_addc_u32 s67, s67, 0
	ds_read_b128 v[224:227], v136 offset:8192
	ds_read_b128 v[180:183], v137
	s_waitcnt lgkmcnt(4)
	v_mfma_f32_16x16x32_bf16 v[116:119], v[164:167], v[228:231], v[116:119]
	v_mfma_f32_16x16x32_bf16 v[124:127], v[168:171], v[228:231], v[124:127]
	v_mfma_f32_16x16x32_bf16 v[100:103], v[172:175], v[228:231], v[100:103]
	v_mfma_f32_16x16x32_bf16 v[108:111], v[176:179], v[228:231], v[108:111]
	s_add_u32 s53, s51, s48
	s_add_u32 m0, s53, 0x4000
	s_nop 0
	global_load_lds_dwordx4 v139, s[68:69]
	s_add_u32 s68, s68, 0x80
	s_addc_u32 s69, s69, 0
	s_add_u32 s53, s51, s48
	s_add_u32 m0, s53, 0x6000
	s_nop 0
	global_load_lds_dwordx4 v139, s[70:71]
	s_add_u32 s70, s70, 0x80
	s_addc_u32 s71, s71, 0
	ds_read_b128 v[228:231], v136 offset:10240
	ds_read_b128 v[212:215], v137 offset:2048
	s_waitcnt lgkmcnt(5)
	v_mfma_f32_16x16x32_bf16 v[80:83], v[164:167], v[232:235], v[80:83]
	v_mfma_f32_16x16x32_bf16 v[88:91], v[168:171], v[232:235], v[88:91]
	v_mfma_f32_16x16x32_bf16 v[64:67], v[172:175], v[232:235], v[64:67]
	v_mfma_f32_16x16x32_bf16 v[72:75], v[176:179], v[232:235], v[72:75]
	s_add_u32 m0, s52, s48
	s_nop 0
	global_load_lds_dwordx4 v138, s[56:57]
	s_add_u32 s56, s56, 0x80
	s_addc_u32 s57, s57, 0
	s_add_u32 s53, s52, s48
	s_add_u32 m0, s53, 0x2000
	s_nop 0
	global_load_lds_dwordx4 v138, s[58:59]
	s_add_u32 s58, s58, 0x80
	s_addc_u32 s59, s59, 0
	ds_read_b128 v[232:235], v136 offset:12288
	ds_read_b128 v[216:219], v137 offset:4096
	s_waitcnt lgkmcnt(6)
	v_mfma_f32_16x16x32_bf16 v[84:87], v[164:167], v[236:239], v[84:87]
	v_mfma_f32_16x16x32_bf16 v[92:95], v[168:171], v[236:239], v[92:95]
	v_mfma_f32_16x16x32_bf16 v[68:71], v[172:175], v[236:239], v[68:71]
	v_mfma_f32_16x16x32_bf16 v[76:79], v[176:179], v[236:239], v[76:79]
	s_add_u32 s53, s52, s48
	s_add_u32 m0, s53, 0x4000
	s_nop 0
	global_load_lds_dwordx4 v138, s[60:61]
	s_add_u32 s60, s60, 0x80
	s_addc_u32 s61, s61, 0
	s_add_u32 s53, s52, s48
	s_add_u32 m0, s53, 0x6000
	s_nop 0
	global_load_lds_dwordx4 v138, s[62:63]
	s_add_u32 s62, s62, 0x80
	s_addc_u32 s63, s63, 0
	ds_read_b128 v[236:239], v136 offset:14336
	ds_read_b128 v[220:223], v137 offset:6144
	v_add_u32_e32 v136, s49, v133
	s_waitcnt lgkmcnt(7)
	v_mfma_f32_16x16x32_bf16 v[48:51], v[164:167], v[224:227], v[48:51]
	v_mfma_f32_16x16x32_bf16 v[56:59], v[168:171], v[224:227], v[56:59]
	v_mfma_f32_16x16x32_bf16 v[32:35], v[172:175], v[224:227], v[32:35]
	v_mfma_f32_16x16x32_bf16 v[40:43], v[176:179], v[224:227], v[40:43]
	ds_read_b128 v[224:227], v136
	s_waitcnt lgkmcnt(6)
	v_mfma_f32_16x16x32_bf16 v[52:55], v[164:167], v[228:231], v[52:55]
	v_mfma_f32_16x16x32_bf16 v[60:63], v[168:171], v[228:231], v[60:63]
	v_mfma_f32_16x16x32_bf16 v[36:39], v[172:175], v[228:231], v[36:39]
	v_mfma_f32_16x16x32_bf16 v[44:47], v[176:179], v[228:231], v[44:47]
	ds_read_b128 v[228:231], v136 offset:2048
	s_waitcnt lgkmcnt(5)
	v_mfma_f32_16x16x32_bf16 v[16:19], v[164:167], v[232:235], v[16:19]
	v_mfma_f32_16x16x32_bf16 v[24:27], v[168:171], v[232:235], v[24:27]
	v_mfma_f32_16x16x32_bf16 v[0:3], v[172:175], v[232:235], v[0:3]
	v_mfma_f32_16x16x32_bf16 v[8:11], v[176:179], v[232:235], v[8:11]
	ds_read_b128 v[232:235], v136 offset:4096
	s_waitcnt lgkmcnt(4)
	v_mfma_f32_16x16x32_bf16 v[20:23], v[164:167], v[236:239], v[20:23]
	v_mfma_f32_16x16x32_bf16 v[28:31], v[168:171], v[236:239], v[28:31]
	v_mfma_f32_16x16x32_bf16 v[4:7], v[172:175], v[236:239], v[4:7]
	v_mfma_f32_16x16x32_bf16 v[12:15], v[176:179], v[236:239], v[12:15]
	ds_read_b128 v[236:239], v136 offset:6144
	s_waitcnt lgkmcnt(4)
	s_waitcnt lgkmcnt(3)
	v_mfma_f32_16x16x32_bf16 v[112:115], v[180:183], v[224:227], v[112:115]
	v_mfma_f32_16x16x32_bf16 v[120:123], v[212:215], v[224:227], v[120:123]
	v_mfma_f32_16x16x32_bf16 v[96:99], v[216:219], v[224:227], v[96:99]
	v_mfma_f32_16x16x32_bf16 v[104:107], v[220:223], v[224:227], v[104:107]
	ds_read_b128 v[224:227], v136 offset:8192
	s_waitcnt lgkmcnt(3)
	v_mfma_f32_16x16x32_bf16 v[116:119], v[180:183], v[228:231], v[116:119]
	v_mfma_f32_16x16x32_bf16 v[124:127], v[212:215], v[228:231], v[124:127]
	v_mfma_f32_16x16x32_bf16 v[100:103], v[216:219], v[228:231], v[100:103]
	v_mfma_f32_16x16x32_bf16 v[108:111], v[220:223], v[228:231], v[108:111]
	ds_read_b128 v[228:231], v136 offset:10240
	s_waitcnt lgkmcnt(3)
	v_mfma_f32_16x16x32_bf16 v[80:83], v[180:183], v[232:235], v[80:83]
	v_mfma_f32_16x16x32_bf16 v[88:91], v[212:215], v[232:235], v[88:91]
	v_mfma_f32_16x16x32_bf16 v[64:67], v[216:219], v[232:235], v[64:67]
	v_mfma_f32_16x16x32_bf16 v[72:75], v[220:223], v[232:235], v[72:75]
	ds_read_b128 v[232:235], v136 offset:12288
	s_waitcnt lgkmcnt(3)
	v_mfma_f32_16x16x32_bf16 v[84:87], v[180:183], v[236:239], v[84:87]
	v_mfma_f32_16x16x32_bf16 v[92:95], v[212:215], v[236:239], v[92:95]
	v_mfma_f32_16x16x32_bf16 v[68:71], v[216:219], v[236:239], v[68:71]
	v_mfma_f32_16x16x32_bf16 v[76:79], v[220:223], v[236:239], v[76:79]
	ds_read_b128 v[236:239], v136 offset:14336
	s_waitcnt lgkmcnt(3)
	v_mfma_f32_16x16x32_bf16 v[48:51], v[180:183], v[224:227], v[48:51]
	v_mfma_f32_16x16x32_bf16 v[56:59], v[212:215], v[224:227], v[56:59]
	v_mfma_f32_16x16x32_bf16 v[32:35], v[216:219], v[224:227], v[32:35]
	v_mfma_f32_16x16x32_bf16 v[40:43], v[220:223], v[224:227], v[40:43]
	s_waitcnt lgkmcnt(2)
	v_mfma_f32_16x16x32_bf16 v[52:55], v[180:183], v[228:231], v[52:55]
	v_mfma_f32_16x16x32_bf16 v[60:63], v[212:215], v[228:231], v[60:63]
	v_mfma_f32_16x16x32_bf16 v[36:39], v[216:219], v[228:231], v[36:39]
	v_mfma_f32_16x16x32_bf16 v[44:47], v[220:223], v[228:231], v[44:47]
	s_waitcnt lgkmcnt(1)
	v_mfma_f32_16x16x32_bf16 v[16:19], v[180:183], v[232:235], v[16:19]
	v_mfma_f32_16x16x32_bf16 v[24:27], v[212:215], v[232:235], v[24:27]
	v_mfma_f32_16x16x32_bf16 v[0:3], v[216:219], v[232:235], v[0:3]
	v_mfma_f32_16x16x32_bf16 v[8:11], v[220:223], v[232:235], v[8:11]
	s_waitcnt lgkmcnt(0)
	s_add_u32 s4, s4, 0x80
	s_addc_u32 s5, s5, 0
	s_add_u32 s49, s49, 0x10000
	s_sub_u32 s53, s49, 0x28000
	s_cmp_ge_u32 s49, 0x28000
	s_cselect_b32 s49, s53, s49
	s_mov_b32 s50, s51
	s_waitcnt vmcnt(4)
	s_barrier
	v_add_u32_e32 v137, s50, v134
	v_add_u32_e32 v136, s49, v132
	ds_read_b128 v[164:167], v137
	ds_read_b128 v[168:171], v137 offset:2048
	ds_read_b128 v[172:175], v137 offset:4096
	ds_read_b128 v[176:179], v137 offset:6144
	ds_read_b128 v[224:227], v136
	ds_read_b128 v[228:231], v136 offset:2048
	ds_read_b128 v[232:235], v136 offset:4096
	v_mfma_f32_16x16x32_bf16 v[20:23], v[180:183], v[236:239], v[20:23]
	v_mfma_f32_16x16x32_bf16 v[28:31], v[212:215], v[236:239], v[28:31]
	v_mfma_f32_16x16x32_bf16 v[4:7], v[216:219], v[236:239], v[4:7]
	v_mfma_f32_16x16x32_bf16 v[12:15], v[220:223], v[236:239], v[12:15]
	ds_read_b128 v[236:239], v136 offset:6144
	s_cmpk_lg_i32 s4, 0xf00
	s_cbranch_scc1 .Lg161_loop
	s_add_u32 s51, s50, 0x10000
	s_sub_u32 s53, s51, 0x28000
	s_cmp_ge_u32 s51, 0x28000
	s_cselect_b32 s51, s53, s51
	v_add_u32_e32 v137, s50, v135
	s_waitcnt lgkmcnt(4)
	s_waitcnt lgkmcnt(3)
	v_mfma_f32_16x16x32_bf16 v[112:115], v[164:167], v[224:227], v[112:115]
	v_mfma_f32_16x16x32_bf16 v[120:123], v[168:171], v[224:227], v[120:123]
	v_mfma_f32_16x16x32_bf16 v[96:99], v[172:175], v[224:227], v[96:99]
	v_mfma_f32_16x16x32_bf16 v[104:107], v[176:179], v[224:227], v[104:107]
	s_add_u32 m0, s51, s48
	s_nop 0
	global_load_lds_dwordx4 v139, s[64:65]
	s_add_u32 s64, s64, 0x80
	s_addc_u32 s65, s65, 0
	s_add_u32 s53, s51, s48
	s_add_u32 m0, s53, 0x2000
	s_nop 0
	global_load_lds_dwordx4 v139, s[66:67]
	s_add_u32 s66, s66, 0x80
	s_addc_u32 s67, s67, 0
	ds_read_b128 v[224:227], v136 offset:8192
	ds_read_b128 v[180:183], v137
	s_waitcnt lgkmcnt(4)
	v_mfma_f32_16x16x32_bf16 v[116:119], v[164:167], v[228:231], v[116:119]
	v_mfma_f32_16x16x32_bf16 v[124:127], v[168:171], v[228:231], v[124:127]
	v_mfma_f32_16x16x32_bf16 v[100:103], v[172:175], v[228:231], v[100:103]
	v_mfma_f32_16x16x32_bf16 v[108:111], v[176:179], v[228:231], v[108:111]
	s_add_u32 s53, s51, s48
	s_add_u32 m0, s53, 0x4000
	s_nop 0
	global_load_lds_dwordx4 v139, s[68:69]
	s_add_u32 s68, s68, 0x80
	s_addc_u32 s69, s69, 0
	s_add_u32 s53, s51, s48
	s_add_u32 m0, s53, 0x6000
	s_nop 0
	global_load_lds_dwordx4 v139, s[70:71]
	s_add_u32 s70, s70, 0x80
	s_addc_u32 s71, s71, 0
	ds_read_b128 v[228:231], v136 offset:10240
	ds_read_b128 v[212:215], v137 offset:2048
	s_waitcnt lgkmcnt(5)
	v_mfma_f32_16x16x32_bf16 v[80:83], v[164:167], v[232:235], v[80:83]
	v_mfma_f32_16x16x32_bf16 v[88:91], v[168:171], v[232:235], v[88:91]
	v_mfma_f32_16x16x32_bf16 v[64:67], v[172:175], v[232:235], v[64:67]
	v_mfma_f32_16x16x32_bf16 v[72:75], v[176:179], v[232:235], v[72:75]
	ds_read_b128 v[232:235], v136 offset:12288
	ds_read_b128 v[216:219], v137 offset:4096
	s_waitcnt lgkmcnt(6)
	v_mfma_f32_16x16x32_bf16 v[84:87], v[164:167], v[236:239], v[84:87]
	v_mfma_f32_16x16x32_bf16 v[92:95], v[168:171], v[236:239], v[92:95]
	v_mfma_f32_16x16x32_bf16 v[68:71], v[172:175], v[236:239], v[68:71]
	v_mfma_f32_16x16x32_bf16 v[76:79], v[176:179], v[236:239], v[76:79]
	ds_read_b128 v[236:239], v136 offset:14336
	ds_read_b128 v[220:223], v137 offset:6144
	v_add_u32_e32 v136, s49, v133
	s_waitcnt lgkmcnt(7)
	v_mfma_f32_16x16x32_bf16 v[48:51], v[164:167], v[224:227], v[48:51]
	v_mfma_f32_16x16x32_bf16 v[56:59], v[168:171], v[224:227], v[56:59]
	v_mfma_f32_16x16x32_bf16 v[32:35], v[172:175], v[224:227], v[32:35]
	v_mfma_f32_16x16x32_bf16 v[40:43], v[176:179], v[224:227], v[40:43]
	ds_read_b128 v[224:227], v136
	s_waitcnt lgkmcnt(6)
	v_mfma_f32_16x16x32_bf16 v[52:55], v[164:167], v[228:231], v[52:55]
	v_mfma_f32_16x16x32_bf16 v[60:63], v[168:171], v[228:231], v[60:63]
	v_mfma_f32_16x16x32_bf16 v[36:39], v[172:175], v[228:231], v[36:39]
	v_mfma_f32_16x16x32_bf16 v[44:47], v[176:179], v[228:231], v[44:47]
	ds_read_b128 v[228:231], v136 offset:2048
	s_waitcnt lgkmcnt(5)
	v_mfma_f32_16x16x32_bf16 v[16:19], v[164:167], v[232:235], v[16:19]
	v_mfma_f32_16x16x32_bf16 v[24:27], v[168:171], v[232:235], v[24:27]
	v_mfma_f32_16x16x32_bf16 v[0:3], v[172:175], v[232:235], v[0:3]
	v_mfma_f32_16x16x32_bf16 v[8:11], v[176:179], v[232:235], v[8:11]
	ds_read_b128 v[232:235], v136 offset:4096
	s_waitcnt lgkmcnt(4)
	v_mfma_f32_16x16x32_bf16 v[20:23], v[164:167], v[236:239], v[20:23]
	v_mfma_f32_16x16x32_bf16 v[28:31], v[168:171], v[236:239], v[28:31]
	v_mfma_f32_16x16x32_bf16 v[4:7], v[172:175], v[236:239], v[4:7]
	v_mfma_f32_16x16x32_bf16 v[12:15], v[176:179], v[236:239], v[12:15]
	ds_read_b128 v[236:239], v136 offset:6144
	s_waitcnt lgkmcnt(4)
	s_waitcnt lgkmcnt(3)
	v_mfma_f32_16x16x32_bf16 v[112:115], v[180:183], v[224:227], v[112:115]
	v_mfma_f32_16x16x32_bf16 v[120:123], v[212:215], v[224:227], v[120:123]
	v_mfma_f32_16x16x32_bf16 v[96:99], v[216:219], v[224:227], v[96:99]
	v_mfma_f32_16x16x32_bf16 v[104:107], v[220:223], v[224:227], v[104:107]
	ds_read_b128 v[224:227], v136 offset:8192
	s_waitcnt lgkmcnt(3)
	v_mfma_f32_16x16x32_bf16 v[116:119], v[180:183], v[228:231], v[116:119]
	v_mfma_f32_16x16x32_bf16 v[124:127], v[212:215], v[228:231], v[124:127]
	v_mfma_f32_16x16x32_bf16 v[100:103], v[216:219], v[228:231], v[100:103]
	v_mfma_f32_16x16x32_bf16 v[108:111], v[220:223], v[228:231], v[108:111]
	ds_read_b128 v[228:231], v136 offset:10240
	s_waitcnt lgkmcnt(3)
	v_mfma_f32_16x16x32_bf16 v[80:83], v[180:183], v[232:235], v[80:83]
	v_mfma_f32_16x16x32_bf16 v[88:91], v[212:215], v[232:235], v[88:91]
	v_mfma_f32_16x16x32_bf16 v[64:67], v[216:219], v[232:235], v[64:67]
	v_mfma_f32_16x16x32_bf16 v[72:75], v[220:223], v[232:235], v[72:75]
	ds_read_b128 v[232:235], v136 offset:12288
	s_waitcnt lgkmcnt(3)
	v_mfma_f32_16x16x32_bf16 v[84:87], v[180:183], v[236:239], v[84:87]
	v_mfma_f32_16x16x32_bf16 v[92:95], v[212:215], v[236:239], v[92:95]
	v_mfma_f32_16x16x32_bf16 v[68:71], v[216:219], v[236:239], v[68:71]
	v_mfma_f32_16x16x32_bf16 v[76:79], v[220:223], v[236:239], v[76:79]
	ds_read_b128 v[236:239], v136 offset:14336
	s_waitcnt lgkmcnt(3)
	v_mfma_f32_16x16x32_bf16 v[48:51], v[180:183], v[224:227], v[48:51]
	v_mfma_f32_16x16x32_bf16 v[56:59], v[212:215], v[224:227], v[56:59]
	v_mfma_f32_16x16x32_bf16 v[32:35], v[216:219], v[224:227], v[32:35]
	v_mfma_f32_16x16x32_bf16 v[40:43], v[220:223], v[224:227], v[40:43]
	s_waitcnt lgkmcnt(2)
	v_mfma_f32_16x16x32_bf16 v[52:55], v[180:183], v[228:231], v[52:55]
	v_mfma_f32_16x16x32_bf16 v[60:63], v[212:215], v[228:231], v[60:63]
	v_mfma_f32_16x16x32_bf16 v[36:39], v[216:219], v[228:231], v[36:39]
	v_mfma_f32_16x16x32_bf16 v[44:47], v[220:223], v[228:231], v[44:47]
	s_waitcnt lgkmcnt(1)
	v_mfma_f32_16x16x32_bf16 v[16:19], v[180:183], v[232:235], v[16:19]
	v_mfma_f32_16x16x32_bf16 v[24:27], v[212:215], v[232:235], v[24:27]
	v_mfma_f32_16x16x32_bf16 v[0:3], v[216:219], v[232:235], v[0:3]
	v_mfma_f32_16x16x32_bf16 v[8:11], v[220:223], v[232:235], v[8:11]
	s_waitcnt lgkmcnt(0)
	s_add_u32 s4, s4, 0x80
	s_addc_u32 s5, s5, 0
	s_add_u32 s49, s49, 0x10000
	s_sub_u32 s53, s49, 0x28000
	s_cmp_ge_u32 s49, 0x28000
	s_cselect_b32 s49, s53, s49
	s_mov_b32 s50, s51
	s_waitcnt vmcnt(0)
	s_barrier
	v_add_u32_e32 v137, s50, v134
	v_add_u32_e32 v136, s49, v132
	ds_read_b128 v[164:167], v137
	ds_read_b128 v[168:171], v137 offset:2048
	ds_read_b128 v[172:175], v137 offset:4096
	ds_read_b128 v[176:179], v137 offset:6144
	ds_read_b128 v[224:227], v136
	ds_read_b128 v[228:231], v136 offset:2048
	ds_read_b128 v[232:235], v136 offset:4096
	v_mfma_f32_16x16x32_bf16 v[20:23], v[180:183], v[236:239], v[20:23]
	v_mfma_f32_16x16x32_bf16 v[28:31], v[212:215], v[236:239], v[28:31]
	v_mfma_f32_16x16x32_bf16 v[4:7], v[216:219], v[236:239], v[4:7]
	v_mfma_f32_16x16x32_bf16 v[12:15], v[220:223], v[236:239], v[12:15]
	ds_read_b128 v[236:239], v136 offset:6144
	v_add_u32_e32 v137, s50, v135
	s_waitcnt lgkmcnt(4)
	s_waitcnt lgkmcnt(3)
	v_mfma_f32_16x16x32_bf16 v[112:115], v[164:167], v[224:227], v[112:115]
	v_mfma_f32_16x16x32_bf16 v[120:123], v[168:171], v[224:227], v[120:123]
	v_mfma_f32_16x16x32_bf16 v[96:99], v[172:175], v[224:227], v[96:99]
	v_mfma_f32_16x16x32_bf16 v[104:107], v[176:179], v[224:227], v[104:107]
	ds_read_b128 v[224:227], v136 offset:8192
	ds_read_b128 v[180:183], v137
	s_waitcnt lgkmcnt(4)
	v_mfma_f32_16x16x32_bf16 v[116:119], v[164:167], v[228:231], v[116:119]
	v_mfma_f32_16x16x32_bf16 v[124:127], v[168:171], v[228:231], v[124:127]
	v_mfma_f32_16x16x32_bf16 v[100:103], v[172:175], v[228:231], v[100:103]
	v_mfma_f32_16x16x32_bf16 v[108:111], v[176:179], v[228:231], v[108:111]
	ds_read_b128 v[228:231], v136 offset:10240
	ds_read_b128 v[212:215], v137 offset:2048
	s_waitcnt lgkmcnt(5)
	v_mfma_f32_16x16x32_bf16 v[80:83], v[164:167], v[232:235], v[80:83]
	v_mfma_f32_16x16x32_bf16 v[88:91], v[168:171], v[232:235], v[88:91]
	v_mfma_f32_16x16x32_bf16 v[64:67], v[172:175], v[232:235], v[64:67]
	v_mfma_f32_16x16x32_bf16 v[72:75], v[176:179], v[232:235], v[72:75]
	ds_read_b128 v[232:235], v136 offset:12288
	ds_read_b128 v[216:219], v137 offset:4096
	s_waitcnt lgkmcnt(6)
	v_mfma_f32_16x16x32_bf16 v[84:87], v[164:167], v[236:239], v[84:87]
	v_mfma_f32_16x16x32_bf16 v[92:95], v[168:171], v[236:239], v[92:95]
	v_mfma_f32_16x16x32_bf16 v[68:71], v[172:175], v[236:239], v[68:71]
	v_mfma_f32_16x16x32_bf16 v[76:79], v[176:179], v[236:239], v[76:79]
	ds_read_b128 v[236:239], v136 offset:14336
	ds_read_b128 v[220:223], v137 offset:6144
	v_add_u32_e32 v136, s49, v133
	s_waitcnt lgkmcnt(7)
	v_mfma_f32_16x16x32_bf16 v[48:51], v[164:167], v[224:227], v[48:51]
	v_mfma_f32_16x16x32_bf16 v[56:59], v[168:171], v[224:227], v[56:59]
	v_mfma_f32_16x16x32_bf16 v[32:35], v[172:175], v[224:227], v[32:35]
	v_mfma_f32_16x16x32_bf16 v[40:43], v[176:179], v[224:227], v[40:43]
	ds_read_b128 v[224:227], v136
	s_waitcnt lgkmcnt(6)
	v_mfma_f32_16x16x32_bf16 v[52:55], v[164:167], v[228:231], v[52:55]
	v_mfma_f32_16x16x32_bf16 v[60:63], v[168:171], v[228:231], v[60:63]
	v_mfma_f32_16x16x32_bf16 v[36:39], v[172:175], v[228:231], v[36:39]
	v_mfma_f32_16x16x32_bf16 v[44:47], v[176:179], v[228:231], v[44:47]
	ds_read_b128 v[228:231], v136 offset:2048
	s_waitcnt lgkmcnt(5)
	v_mfma_f32_16x16x32_bf16 v[16:19], v[164:167], v[232:235], v[16:19]
	v_mfma_f32_16x16x32_bf16 v[24:27], v[168:171], v[232:235], v[24:27]
	v_mfma_f32_16x16x32_bf16 v[0:3], v[172:175], v[232:235], v[0:3]
	v_mfma_f32_16x16x32_bf16 v[8:11], v[176:179], v[232:235], v[8:11]
	ds_read_b128 v[232:235], v136 offset:4096
	s_waitcnt lgkmcnt(4)
	v_mfma_f32_16x16x32_bf16 v[20:23], v[164:167], v[236:239], v[20:23]
	v_mfma_f32_16x16x32_bf16 v[28:31], v[168:171], v[236:239], v[28:31]
	v_mfma_f32_16x16x32_bf16 v[4:7], v[172:175], v[236:239], v[4:7]
	v_mfma_f32_16x16x32_bf16 v[12:15], v[176:179], v[236:239], v[12:15]
	ds_read_b128 v[236:239], v136 offset:6144
	s_waitcnt lgkmcnt(4)
	s_waitcnt lgkmcnt(3)
	v_mfma_f32_16x16x32_bf16 v[112:115], v[180:183], v[224:227], v[112:115]
	v_mfma_f32_16x16x32_bf16 v[120:123], v[212:215], v[224:227], v[120:123]
	v_mfma_f32_16x16x32_bf16 v[96:99], v[216:219], v[224:227], v[96:99]
	v_mfma_f32_16x16x32_bf16 v[104:107], v[220:223], v[224:227], v[104:107]
	ds_read_b128 v[224:227], v136 offset:8192
	s_waitcnt lgkmcnt(3)
	v_mfma_f32_16x16x32_bf16 v[116:119], v[180:183], v[228:231], v[116:119]
	v_mfma_f32_16x16x32_bf16 v[124:127], v[212:215], v[228:231], v[124:127]
	v_mfma_f32_16x16x32_bf16 v[100:103], v[216:219], v[228:231], v[100:103]
	v_mfma_f32_16x16x32_bf16 v[108:111], v[220:223], v[228:231], v[108:111]
	ds_read_b128 v[228:231], v136 offset:10240
	s_waitcnt lgkmcnt(3)
	v_mfma_f32_16x16x32_bf16 v[80:83], v[180:183], v[232:235], v[80:83]
	v_mfma_f32_16x16x32_bf16 v[88:91], v[212:215], v[232:235], v[88:91]
	v_mfma_f32_16x16x32_bf16 v[64:67], v[216:219], v[232:235], v[64:67]
	v_mfma_f32_16x16x32_bf16 v[72:75], v[220:223], v[232:235], v[72:75]
	ds_read_b128 v[232:235], v136 offset:12288
	s_waitcnt lgkmcnt(3)
	v_mfma_f32_16x16x32_bf16 v[84:87], v[180:183], v[236:239], v[84:87]
	v_mfma_f32_16x16x32_bf16 v[92:95], v[212:215], v[236:239], v[92:95]
	v_mfma_f32_16x16x32_bf16 v[68:71], v[216:219], v[236:239], v[68:71]
	v_mfma_f32_16x16x32_bf16 v[76:79], v[220:223], v[236:239], v[76:79]
	ds_read_b128 v[236:239], v136 offset:14336
	s_waitcnt lgkmcnt(3)
	v_mfma_f32_16x16x32_bf16 v[48:51], v[180:183], v[224:227], v[48:51]
	v_mfma_f32_16x16x32_bf16 v[56:59], v[212:215], v[224:227], v[56:59]
	v_mfma_f32_16x16x32_bf16 v[32:35], v[216:219], v[224:227], v[32:35]
	v_mfma_f32_16x16x32_bf16 v[40:43], v[220:223], v[224:227], v[40:43]
	s_waitcnt lgkmcnt(2)
	v_mfma_f32_16x16x32_bf16 v[52:55], v[180:183], v[228:231], v[52:55]
	v_mfma_f32_16x16x32_bf16 v[60:63], v[212:215], v[228:231], v[60:63]
	v_mfma_f32_16x16x32_bf16 v[36:39], v[216:219], v[228:231], v[36:39]
	v_mfma_f32_16x16x32_bf16 v[44:47], v[220:223], v[228:231], v[44:47]
	s_waitcnt lgkmcnt(1)
	v_mfma_f32_16x16x32_bf16 v[16:19], v[180:183], v[232:235], v[16:19]
	v_mfma_f32_16x16x32_bf16 v[24:27], v[212:215], v[232:235], v[24:27]
	v_mfma_f32_16x16x32_bf16 v[0:3], v[216:219], v[232:235], v[0:3]
	v_mfma_f32_16x16x32_bf16 v[8:11], v[220:223], v[232:235], v[8:11]
	s_waitcnt lgkmcnt(0)
	s_waitcnt vmcnt(0)
	s_barrier
	v_mfma_f32_16x16x32_bf16 v[20:23], v[180:183], v[236:239], v[20:23]
	v_mfma_f32_16x16x32_bf16 v[28:31], v[212:215], v[236:239], v[28:31]
	v_mfma_f32_16x16x32_bf16 v[4:7], v[216:219], v[236:239], v[4:7]
	v_mfma_f32_16x16x32_bf16 v[12:15], v[220:223], v[236:239], v[12:15]
	s_nop 15
	v_permlane16_swap_b32_e32 v112, v116
	v_permlane16_swap_b32_e32 v113, v117
	v_permlane16_swap_b32_e32 v114, v118
	v_permlane16_swap_b32_e32 v115, v119
	v_permlane16_swap_b32_e32 v120, v124
	v_permlane16_swap_b32_e32 v121, v125
	v_permlane16_swap_b32_e32 v122, v126
	v_permlane16_swap_b32_e32 v123, v127
	v_permlane16_swap_b32_e32 v96, v100
	v_permlane16_swap_b32_e32 v97, v101
	v_permlane16_swap_b32_e32 v98, v102
	v_permlane16_swap_b32_e32 v99, v103
	v_permlane16_swap_b32_e32 v104, v108
	v_permlane16_swap_b32_e32 v105, v109
	v_permlane16_swap_b32_e32 v106, v110
	v_permlane16_swap_b32_e32 v107, v111
	v_permlane16_swap_b32_e32 v80, v84
	v_permlane16_swap_b32_e32 v81, v85
	v_permlane16_swap_b32_e32 v82, v86
	v_permlane16_swap_b32_e32 v83, v87
	v_permlane16_swap_b32_e32 v88, v92
	v_permlane16_swap_b32_e32 v89, v93
	v_permlane16_swap_b32_e32 v90, v94
	v_permlane16_swap_b32_e32 v91, v95
	v_permlane16_swap_b32_e32 v64, v68
	v_permlane16_swap_b32_e32 v65, v69
	v_permlane16_swap_b32_e32 v66, v70
	v_permlane16_swap_b32_e32 v67, v71
	v_permlane16_swap_b32_e32 v72, v76
	v_permlane16_swap_b32_e32 v73, v77
	v_permlane16_swap_b32_e32 v74, v78
	v_permlane16_swap_b32_e32 v75, v79
	v_permlane16_swap_b32_e32 v48, v52
	v_permlane16_swap_b32_e32 v49, v53
	v_permlane16_swap_b32_e32 v50, v54
	v_permlane16_swap_b32_e32 v51, v55
	v_permlane16_swap_b32_e32 v56, v60
	v_permlane16_swap_b32_e32 v57, v61
	v_permlane16_swap_b32_e32 v58, v62
	v_permlane16_swap_b32_e32 v59, v63
	v_permlane16_swap_b32_e32 v32, v36
	v_permlane16_swap_b32_e32 v33, v37
	v_permlane16_swap_b32_e32 v34, v38
	v_permlane16_swap_b32_e32 v35, v39
	v_permlane16_swap_b32_e32 v40, v44
	v_permlane16_swap_b32_e32 v41, v45
	v_permlane16_swap_b32_e32 v42, v46
	v_permlane16_swap_b32_e32 v43, v47
	v_permlane16_swap_b32_e32 v16, v20
	v_permlane16_swap_b32_e32 v17, v21
	v_permlane16_swap_b32_e32 v18, v22
	v_permlane16_swap_b32_e32 v19, v23
	v_permlane16_swap_b32_e32 v24, v28
	v_permlane16_swap_b32_e32 v25, v29
	v_permlane16_swap_b32_e32 v26, v30
	v_permlane16_swap_b32_e32 v27, v31
	v_permlane16_swap_b32_e32 v0, v4
	v_permlane16_swap_b32_e32 v1, v5
	v_permlane16_swap_b32_e32 v2, v6
	v_permlane16_swap_b32_e32 v3, v7
	v_permlane16_swap_b32_e32 v8, v12
	v_permlane16_swap_b32_e32 v9, v13
	v_permlane16_swap_b32_e32 v10, v14
	v_permlane16_swap_b32_e32 v11, v15
	v_permlane32_swap_b32_e32 v112, v116
	v_permlane32_swap_b32_e32 v113, v117
	v_permlane32_swap_b32_e32 v114, v118
	v_permlane32_swap_b32_e32 v115, v119
	v_permlane32_swap_b32_e32 v120, v124
	v_permlane32_swap_b32_e32 v121, v125
	v_permlane32_swap_b32_e32 v122, v126
	v_permlane32_swap_b32_e32 v123, v127
	v_permlane32_swap_b32_e32 v96, v100
	v_permlane32_swap_b32_e32 v97, v101
	v_permlane32_swap_b32_e32 v98, v102
	v_permlane32_swap_b32_e32 v99, v103
	v_permlane32_swap_b32_e32 v104, v108
	v_permlane32_swap_b32_e32 v105, v109
	v_permlane32_swap_b32_e32 v106, v110
	v_permlane32_swap_b32_e32 v107, v111
	v_permlane32_swap_b32_e32 v80, v84
	v_permlane32_swap_b32_e32 v81, v85
	v_permlane32_swap_b32_e32 v82, v86
	v_permlane32_swap_b32_e32 v83, v87
	v_permlane32_swap_b32_e32 v88, v92
	v_permlane32_swap_b32_e32 v89, v93
	v_permlane32_swap_b32_e32 v90, v94
	v_permlane32_swap_b32_e32 v91, v95
	v_permlane32_swap_b32_e32 v64, v68
	v_permlane32_swap_b32_e32 v65, v69
	v_permlane32_swap_b32_e32 v66, v70
	v_permlane32_swap_b32_e32 v67, v71
	v_permlane32_swap_b32_e32 v72, v76
	v_permlane32_swap_b32_e32 v73, v77
	v_permlane32_swap_b32_e32 v74, v78
	v_permlane32_swap_b32_e32 v75, v79
	v_permlane32_swap_b32_e32 v48, v52
	v_permlane32_swap_b32_e32 v49, v53
	v_permlane32_swap_b32_e32 v50, v54
	v_permlane32_swap_b32_e32 v51, v55
	v_permlane32_swap_b32_e32 v56, v60
	v_permlane32_swap_b32_e32 v57, v61
	v_permlane32_swap_b32_e32 v58, v62
	v_permlane32_swap_b32_e32 v59, v63
	v_permlane32_swap_b32_e32 v32, v36
	v_permlane32_swap_b32_e32 v33, v37
	v_permlane32_swap_b32_e32 v34, v38
	v_permlane32_swap_b32_e32 v35, v39
	v_permlane32_swap_b32_e32 v40, v44
	v_permlane32_swap_b32_e32 v41, v45
	v_permlane32_swap_b32_e32 v42, v46
	v_permlane32_swap_b32_e32 v43, v47
	v_permlane32_swap_b32_e32 v16, v20
	v_permlane32_swap_b32_e32 v17, v21
	v_permlane32_swap_b32_e32 v18, v22
	v_permlane32_swap_b32_e32 v19, v23
	v_permlane32_swap_b32_e32 v24, v28
	v_permlane32_swap_b32_e32 v25, v29
	v_permlane32_swap_b32_e32 v26, v30
	v_permlane32_swap_b32_e32 v27, v31
	v_permlane32_swap_b32_e32 v0, v4
	v_permlane32_swap_b32_e32 v1, v5
	v_permlane32_swap_b32_e32 v2, v6
	v_permlane32_swap_b32_e32 v3, v7
	v_permlane32_swap_b32_e32 v8, v12
	v_permlane32_swap_b32_e32 v9, v13
	v_permlane32_swap_b32_e32 v10, v14
	v_permlane32_swap_b32_e32 v11, v15
	s_nop 1

.Lg162_loop:
	s_add_u32 s51, s50, 0x10000
	s_sub_u32 s53, s51, 0x28000
	s_cmp_ge_u32 s51, 0x28000
	s_cselect_b32 s51, s53, s51
	s_add_u32 s52, s49, 0x20000
	s_sub_u32 s53, s52, 0x28000
	s_cmp_ge_u32 s52, 0x28000
	s_cselect_b32 s52, s53, s52
	v_add_u32_e32 v167, s50, v145
	s_waitcnt lgkmcnt(4)
	s_waitcnt lgkmcnt(3)
	v_mfma_f32_16x16x32_bf16 v[112:115], v[188:191], v[220:223], v[112:115]
	v_mfma_f32_16x16x32_bf16 v[120:123], v[192:195], v[220:223], v[120:123]
	v_mfma_f32_16x16x32_bf16 v[96:99], v[196:199], v[220:223], v[96:99]
	v_mfma_f32_16x16x32_bf16 v[104:107], v[200:203], v[220:223], v[104:107]
	s_add_u32 m0, s51, s48
	s_nop 0
	global_load_lds_dwordx4 v169, s[64:65]
	s_add_u32 s64, s64, 0x80
	s_addc_u32 s65, s65, 0
	s_add_u32 s53, s51, s48
	s_add_u32 m0, s53, 0x2000
	s_nop 0
	global_load_lds_dwordx4 v169, s[66:67]
	s_add_u32 s66, s66, 0x80
	s_addc_u32 s67, s67, 0
	ds_read_b128 v[220:223], v166 offset:8192
	ds_read_b128 v[204:207], v167
	s_waitcnt lgkmcnt(4)
	v_mfma_f32_16x16x32_bf16 v[116:119], v[188:191], v[224:227], v[116:119]
	v_mfma_f32_16x16x32_bf16 v[124:127], v[192:195], v[224:227], v[124:127]
	v_mfma_f32_16x16x32_bf16 v[100:103], v[196:199], v[224:227], v[100:103]
	v_mfma_f32_16x16x32_bf16 v[108:111], v[200:203], v[224:227], v[108:111]
	s_add_u32 s53, s51, s48
	s_add_u32 m0, s53, 0x4000
	s_nop 0
	global_load_lds_dwordx4 v169, s[68:69]
	s_add_u32 s68, s68, 0x80
	s_addc_u32 s69, s69, 0
	s_add_u32 s53, s51, s48
	s_add_u32 m0, s53, 0x6000
	s_nop 0
	global_load_lds_dwordx4 v169, s[70:71]
	s_add_u32 s70, s70, 0x80
	s_addc_u32 s71, s71, 0
	ds_read_b128 v[224:227], v166 offset:10240
	ds_read_b128 v[208:211], v167 offset:2048
	s_waitcnt lgkmcnt(5)
	v_mfma_f32_16x16x32_bf16 v[80:83], v[188:191], v[228:231], v[80:83]
	v_mfma_f32_16x16x32_bf16 v[88:91], v[192:195], v[228:231], v[88:91]
	v_mfma_f32_16x16x32_bf16 v[64:67], v[196:199], v[228:231], v[64:67]
	v_mfma_f32_16x16x32_bf16 v[72:75], v[200:203], v[228:231], v[72:75]
	s_add_u32 m0, s52, s48
	s_nop 0
	global_load_lds_dwordx4 v168, s[56:57]
	s_add_u32 s56, s56, 0x80
	s_addc_u32 s57, s57, 0
	s_add_u32 s53, s52, s48
	s_add_u32 m0, s53, 0x2000
	s_nop 0
	global_load_lds_dwordx4 v168, s[58:59]
	s_add_u32 s58, s58, 0x80
	s_addc_u32 s59, s59, 0
	ds_read_b128 v[228:231], v166 offset:12288
	ds_read_b128 v[212:215], v167 offset:4096
	s_waitcnt lgkmcnt(6)
	v_mfma_f32_16x16x32_bf16 v[84:87], v[188:191], v[232:235], v[84:87]
	v_mfma_f32_16x16x32_bf16 v[92:95], v[192:195], v[232:235], v[92:95]
	v_mfma_f32_16x16x32_bf16 v[68:71], v[196:199], v[232:235], v[68:71]
	v_mfma_f32_16x16x32_bf16 v[76:79], v[200:203], v[232:235], v[76:79]
	s_add_u32 s53, s52, s48
	s_add_u32 m0, s53, 0x4000
	s_nop 0
	global_load_lds_dwordx4 v168, s[60:61]
	s_add_u32 s60, s60, 0x80
	s_addc_u32 s61, s61, 0
	s_add_u32 s53, s52, s48
	s_add_u32 m0, s53, 0x6000
	s_nop 0
	global_load_lds_dwordx4 v168, s[62:63]
	s_add_u32 s62, s62, 0x80
	s_addc_u32 s63, s63, 0
	ds_read_b128 v[232:235], v166 offset:14336
	ds_read_b128 v[216:219], v167 offset:6144
	v_add_u32_e32 v166, s49, v143
	s_waitcnt lgkmcnt(7)
	v_mfma_f32_16x16x32_bf16 v[48:51], v[188:191], v[220:223], v[48:51]
	v_mfma_f32_16x16x32_bf16 v[56:59], v[192:195], v[220:223], v[56:59]
	v_mfma_f32_16x16x32_bf16 v[32:35], v[196:199], v[220:223], v[32:35]
	v_mfma_f32_16x16x32_bf16 v[40:43], v[200:203], v[220:223], v[40:43]
	ds_read_b128 v[220:223], v166
	s_waitcnt lgkmcnt(6)
	v_mfma_f32_16x16x32_bf16 v[52:55], v[188:191], v[224:227], v[52:55]
	v_mfma_f32_16x16x32_bf16 v[60:63], v[192:195], v[224:227], v[60:63]
	v_mfma_f32_16x16x32_bf16 v[36:39], v[196:199], v[224:227], v[36:39]
	v_mfma_f32_16x16x32_bf16 v[44:47], v[200:203], v[224:227], v[44:47]
	ds_read_b128 v[224:227], v166 offset:2048
	s_waitcnt lgkmcnt(5)
	v_mfma_f32_16x16x32_bf16 v[16:19], v[188:191], v[228:231], v[16:19]
	v_mfma_f32_16x16x32_bf16 v[24:27], v[192:195], v[228:231], v[24:27]
	v_mfma_f32_16x16x32_bf16 v[0:3], v[196:199], v[228:231], v[0:3]
	v_mfma_f32_16x16x32_bf16 v[8:11], v[200:203], v[228:231], v[8:11]
	ds_read_b128 v[228:231], v166 offset:4096
	s_waitcnt lgkmcnt(4)
	v_mfma_f32_16x16x32_bf16 v[20:23], v[188:191], v[232:235], v[20:23]
	v_mfma_f32_16x16x32_bf16 v[28:31], v[192:195], v[232:235], v[28:31]
	v_mfma_f32_16x16x32_bf16 v[4:7], v[196:199], v[232:235], v[4:7]
	v_mfma_f32_16x16x32_bf16 v[12:15], v[200:203], v[232:235], v[12:15]
	ds_read_b128 v[232:235], v166 offset:6144
	s_waitcnt lgkmcnt(4)
	s_waitcnt lgkmcnt(3)
	v_mfma_f32_16x16x32_bf16 v[112:115], v[204:207], v[220:223], v[112:115]
	v_mfma_f32_16x16x32_bf16 v[120:123], v[208:211], v[220:223], v[120:123]
	v_mfma_f32_16x16x32_bf16 v[96:99], v[212:215], v[220:223], v[96:99]
	v_mfma_f32_16x16x32_bf16 v[104:107], v[216:219], v[220:223], v[104:107]
	ds_read_b128 v[220:223], v166 offset:8192
	s_waitcnt lgkmcnt(3)
	v_mfma_f32_16x16x32_bf16 v[116:119], v[204:207], v[224:227], v[116:119]
	v_mfma_f32_16x16x32_bf16 v[124:127], v[208:211], v[224:227], v[124:127]
	v_mfma_f32_16x16x32_bf16 v[100:103], v[212:215], v[224:227], v[100:103]
	v_mfma_f32_16x16x32_bf16 v[108:111], v[216:219], v[224:227], v[108:111]
	ds_read_b128 v[224:227], v166 offset:10240
	s_waitcnt lgkmcnt(3)
	v_mfma_f32_16x16x32_bf16 v[80:83], v[204:207], v[228:231], v[80:83]
	v_mfma_f32_16x16x32_bf16 v[88:91], v[208:211], v[228:231], v[88:91]
	v_mfma_f32_16x16x32_bf16 v[64:67], v[212:215], v[228:231], v[64:67]
	v_mfma_f32_16x16x32_bf16 v[72:75], v[216:219], v[228:231], v[72:75]
	ds_read_b128 v[228:231], v166 offset:12288
	s_waitcnt lgkmcnt(3)
	v_mfma_f32_16x16x32_bf16 v[84:87], v[204:207], v[232:235], v[84:87]
	v_mfma_f32_16x16x32_bf16 v[92:95], v[208:211], v[232:235], v[92:95]
	v_mfma_f32_16x16x32_bf16 v[68:71], v[212:215], v[232:235], v[68:71]
	v_mfma_f32_16x16x32_bf16 v[76:79], v[216:219], v[232:235], v[76:79]
	ds_read_b128 v[232:235], v166 offset:14336
	s_waitcnt lgkmcnt(3)
	v_mfma_f32_16x16x32_bf16 v[48:51], v[204:207], v[220:223], v[48:51]
	v_mfma_f32_16x16x32_bf16 v[56:59], v[208:211], v[220:223], v[56:59]
	v_mfma_f32_16x16x32_bf16 v[32:35], v[212:215], v[220:223], v[32:35]
	v_mfma_f32_16x16x32_bf16 v[40:43], v[216:219], v[220:223], v[40:43]
	s_waitcnt lgkmcnt(2)
	v_mfma_f32_16x16x32_bf16 v[52:55], v[204:207], v[224:227], v[52:55]
	v_mfma_f32_16x16x32_bf16 v[60:63], v[208:211], v[224:227], v[60:63]
	v_mfma_f32_16x16x32_bf16 v[36:39], v[212:215], v[224:227], v[36:39]
	v_mfma_f32_16x16x32_bf16 v[44:47], v[216:219], v[224:227], v[44:47]
	s_waitcnt lgkmcnt(1)
	v_mfma_f32_16x16x32_bf16 v[16:19], v[204:207], v[228:231], v[16:19]
	v_mfma_f32_16x16x32_bf16 v[24:27], v[208:211], v[228:231], v[24:27]
	v_mfma_f32_16x16x32_bf16 v[0:3], v[212:215], v[228:231], v[0:3]
	v_mfma_f32_16x16x32_bf16 v[8:11], v[216:219], v[228:231], v[8:11]
	s_waitcnt lgkmcnt(0)
	s_add_u32 s28, s28, 0x80
	s_addc_u32 s29, s29, 0
	s_add_u32 s49, s49, 0x10000
	s_sub_u32 s53, s49, 0x28000
	s_cmp_ge_u32 s49, 0x28000
	s_cselect_b32 s49, s53, s49
	s_mov_b32 s50, s51
	s_waitcnt vmcnt(4)
	s_barrier
	v_add_u32_e32 v167, s50, v144
	v_add_u32_e32 v166, s49, v142
	ds_read_b128 v[188:191], v167
	ds_read_b128 v[192:195], v167 offset:2048
	ds_read_b128 v[196:199], v167 offset:4096
	ds_read_b128 v[200:203], v167 offset:6144
	ds_read_b128 v[220:223], v166
	ds_read_b128 v[224:227], v166 offset:2048
	ds_read_b128 v[228:231], v166 offset:4096
	v_mfma_f32_16x16x32_bf16 v[20:23], v[204:207], v[232:235], v[20:23]
	v_mfma_f32_16x16x32_bf16 v[28:31], v[208:211], v[232:235], v[28:31]
	v_mfma_f32_16x16x32_bf16 v[4:7], v[212:215], v[232:235], v[4:7]
	v_mfma_f32_16x16x32_bf16 v[12:15], v[216:219], v[232:235], v[12:15]
	ds_read_b128 v[232:235], v166 offset:6144
	s_cmpk_lg_i32 s28, 0xf00
	s_cbranch_scc1 .Lg162_loop
	s_add_u32 s51, s50, 0x10000
	s_sub_u32 s53, s51, 0x28000
	s_cmp_ge_u32 s51, 0x28000
	s_cselect_b32 s51, s53, s51
	v_add_u32_e32 v167, s50, v145
	s_waitcnt lgkmcnt(4)
	s_waitcnt lgkmcnt(3)
	v_mfma_f32_16x16x32_bf16 v[112:115], v[188:191], v[220:223], v[112:115]
	v_mfma_f32_16x16x32_bf16 v[120:123], v[192:195], v[220:223], v[120:123]
	v_mfma_f32_16x16x32_bf16 v[96:99], v[196:199], v[220:223], v[96:99]
	v_mfma_f32_16x16x32_bf16 v[104:107], v[200:203], v[220:223], v[104:107]
	s_add_u32 m0, s51, s48
	s_nop 0
	global_load_lds_dwordx4 v169, s[64:65]
	s_add_u32 s64, s64, 0x80
	s_addc_u32 s65, s65, 0
	s_add_u32 s53, s51, s48
	s_add_u32 m0, s53, 0x2000
	s_nop 0
	global_load_lds_dwordx4 v169, s[66:67]
	s_add_u32 s66, s66, 0x80
	s_addc_u32 s67, s67, 0
	ds_read_b128 v[220:223], v166 offset:8192
	ds_read_b128 v[204:207], v167
	s_waitcnt lgkmcnt(4)
	v_mfma_f32_16x16x32_bf16 v[116:119], v[188:191], v[224:227], v[116:119]
	v_mfma_f32_16x16x32_bf16 v[124:127], v[192:195], v[224:227], v[124:127]
	v_mfma_f32_16x16x32_bf16 v[100:103], v[196:199], v[224:227], v[100:103]
	v_mfma_f32_16x16x32_bf16 v[108:111], v[200:203], v[224:227], v[108:111]
	s_add_u32 s53, s51, s48
	s_add_u32 m0, s53, 0x4000
	s_nop 0
	global_load_lds_dwordx4 v169, s[68:69]
	s_add_u32 s68, s68, 0x80
	s_addc_u32 s69, s69, 0
	s_add_u32 s53, s51, s48
	s_add_u32 m0, s53, 0x6000
	s_nop 0
	global_load_lds_dwordx4 v169, s[70:71]
	s_add_u32 s70, s70, 0x80
	s_addc_u32 s71, s71, 0
	ds_read_b128 v[224:227], v166 offset:10240
	ds_read_b128 v[208:211], v167 offset:2048
	s_waitcnt lgkmcnt(5)
	v_mfma_f32_16x16x32_bf16 v[80:83], v[188:191], v[228:231], v[80:83]
	v_mfma_f32_16x16x32_bf16 v[88:91], v[192:195], v[228:231], v[88:91]
	v_mfma_f32_16x16x32_bf16 v[64:67], v[196:199], v[228:231], v[64:67]
	v_mfma_f32_16x16x32_bf16 v[72:75], v[200:203], v[228:231], v[72:75]
	ds_read_b128 v[228:231], v166 offset:12288
	ds_read_b128 v[212:215], v167 offset:4096
	s_waitcnt lgkmcnt(6)
	v_mfma_f32_16x16x32_bf16 v[84:87], v[188:191], v[232:235], v[84:87]
	v_mfma_f32_16x16x32_bf16 v[92:95], v[192:195], v[232:235], v[92:95]
	v_mfma_f32_16x16x32_bf16 v[68:71], v[196:199], v[232:235], v[68:71]
	v_mfma_f32_16x16x32_bf16 v[76:79], v[200:203], v[232:235], v[76:79]
	ds_read_b128 v[232:235], v166 offset:14336
	ds_read_b128 v[216:219], v167 offset:6144
	v_add_u32_e32 v166, s49, v143
	s_waitcnt lgkmcnt(7)
	v_mfma_f32_16x16x32_bf16 v[48:51], v[188:191], v[220:223], v[48:51]
	v_mfma_f32_16x16x32_bf16 v[56:59], v[192:195], v[220:223], v[56:59]
	v_mfma_f32_16x16x32_bf16 v[32:35], v[196:199], v[220:223], v[32:35]
	v_mfma_f32_16x16x32_bf16 v[40:43], v[200:203], v[220:223], v[40:43]
	ds_read_b128 v[220:223], v166
	s_waitcnt lgkmcnt(6)
	v_mfma_f32_16x16x32_bf16 v[52:55], v[188:191], v[224:227], v[52:55]
	v_mfma_f32_16x16x32_bf16 v[60:63], v[192:195], v[224:227], v[60:63]
	v_mfma_f32_16x16x32_bf16 v[36:39], v[196:199], v[224:227], v[36:39]
	v_mfma_f32_16x16x32_bf16 v[44:47], v[200:203], v[224:227], v[44:47]
	ds_read_b128 v[224:227], v166 offset:2048
	s_waitcnt lgkmcnt(5)
	v_mfma_f32_16x16x32_bf16 v[16:19], v[188:191], v[228:231], v[16:19]
	v_mfma_f32_16x16x32_bf16 v[24:27], v[192:195], v[228:231], v[24:27]
	v_mfma_f32_16x16x32_bf16 v[0:3], v[196:199], v[228:231], v[0:3]
	v_mfma_f32_16x16x32_bf16 v[8:11], v[200:203], v[228:231], v[8:11]
	ds_read_b128 v[228:231], v166 offset:4096
	s_waitcnt lgkmcnt(4)
	v_mfma_f32_16x16x32_bf16 v[20:23], v[188:191], v[232:235], v[20:23]
	v_mfma_f32_16x16x32_bf16 v[28:31], v[192:195], v[232:235], v[28:31]
	v_mfma_f32_16x16x32_bf16 v[4:7], v[196:199], v[232:235], v[4:7]
	v_mfma_f32_16x16x32_bf16 v[12:15], v[200:203], v[232:235], v[12:15]
	ds_read_b128 v[232:235], v166 offset:6144
	s_waitcnt lgkmcnt(4)
	s_waitcnt lgkmcnt(3)
	v_mfma_f32_16x16x32_bf16 v[112:115], v[204:207], v[220:223], v[112:115]
	v_mfma_f32_16x16x32_bf16 v[120:123], v[208:211], v[220:223], v[120:123]
	v_mfma_f32_16x16x32_bf16 v[96:99], v[212:215], v[220:223], v[96:99]
	v_mfma_f32_16x16x32_bf16 v[104:107], v[216:219], v[220:223], v[104:107]
	ds_read_b128 v[220:223], v166 offset:8192
	s_waitcnt lgkmcnt(3)
	v_mfma_f32_16x16x32_bf16 v[116:119], v[204:207], v[224:227], v[116:119]
	v_mfma_f32_16x16x32_bf16 v[124:127], v[208:211], v[224:227], v[124:127]
	v_mfma_f32_16x16x32_bf16 v[100:103], v[212:215], v[224:227], v[100:103]
	v_mfma_f32_16x16x32_bf16 v[108:111], v[216:219], v[224:227], v[108:111]
	ds_read_b128 v[224:227], v166 offset:10240
	s_waitcnt lgkmcnt(3)
	v_mfma_f32_16x16x32_bf16 v[80:83], v[204:207], v[228:231], v[80:83]
	v_mfma_f32_16x16x32_bf16 v[88:91], v[208:211], v[228:231], v[88:91]
	v_mfma_f32_16x16x32_bf16 v[64:67], v[212:215], v[228:231], v[64:67]
	v_mfma_f32_16x16x32_bf16 v[72:75], v[216:219], v[228:231], v[72:75]
	ds_read_b128 v[228:231], v166 offset:12288
	s_waitcnt lgkmcnt(3)
	v_mfma_f32_16x16x32_bf16 v[84:87], v[204:207], v[232:235], v[84:87]
	v_mfma_f32_16x16x32_bf16 v[92:95], v[208:211], v[232:235], v[92:95]
	v_mfma_f32_16x16x32_bf16 v[68:71], v[212:215], v[232:235], v[68:71]
	v_mfma_f32_16x16x32_bf16 v[76:79], v[216:219], v[232:235], v[76:79]
	ds_read_b128 v[232:235], v166 offset:14336
	s_waitcnt lgkmcnt(3)
	v_mfma_f32_16x16x32_bf16 v[48:51], v[204:207], v[220:223], v[48:51]
	v_mfma_f32_16x16x32_bf16 v[56:59], v[208:211], v[220:223], v[56:59]
	v_mfma_f32_16x16x32_bf16 v[32:35], v[212:215], v[220:223], v[32:35]
	v_mfma_f32_16x16x32_bf16 v[40:43], v[216:219], v[220:223], v[40:43]
	s_waitcnt lgkmcnt(2)
	v_mfma_f32_16x16x32_bf16 v[52:55], v[204:207], v[224:227], v[52:55]
	v_mfma_f32_16x16x32_bf16 v[60:63], v[208:211], v[224:227], v[60:63]
	v_mfma_f32_16x16x32_bf16 v[36:39], v[212:215], v[224:227], v[36:39]
	v_mfma_f32_16x16x32_bf16 v[44:47], v[216:219], v[224:227], v[44:47]
	s_waitcnt lgkmcnt(1)
	v_mfma_f32_16x16x32_bf16 v[16:19], v[204:207], v[228:231], v[16:19]
	v_mfma_f32_16x16x32_bf16 v[24:27], v[208:211], v[228:231], v[24:27]
	v_mfma_f32_16x16x32_bf16 v[0:3], v[212:215], v[228:231], v[0:3]
	v_mfma_f32_16x16x32_bf16 v[8:11], v[216:219], v[228:231], v[8:11]
	s_waitcnt lgkmcnt(0)
	s_add_u32 s28, s28, 0x80
	s_addc_u32 s29, s29, 0
	s_add_u32 s49, s49, 0x10000
	s_sub_u32 s53, s49, 0x28000
	s_cmp_ge_u32 s49, 0x28000
	s_cselect_b32 s49, s53, s49
	s_mov_b32 s50, s51
	s_waitcnt vmcnt(0)
	s_barrier
	v_add_u32_e32 v167, s50, v144
	v_add_u32_e32 v166, s49, v142
	ds_read_b128 v[188:191], v167
	ds_read_b128 v[192:195], v167 offset:2048
	ds_read_b128 v[196:199], v167 offset:4096
	ds_read_b128 v[200:203], v167 offset:6144
	ds_read_b128 v[220:223], v166
	ds_read_b128 v[224:227], v166 offset:2048
	ds_read_b128 v[228:231], v166 offset:4096
	v_mfma_f32_16x16x32_bf16 v[20:23], v[204:207], v[232:235], v[20:23]
	v_mfma_f32_16x16x32_bf16 v[28:31], v[208:211], v[232:235], v[28:31]
	v_mfma_f32_16x16x32_bf16 v[4:7], v[212:215], v[232:235], v[4:7]
	v_mfma_f32_16x16x32_bf16 v[12:15], v[216:219], v[232:235], v[12:15]
	ds_read_b128 v[232:235], v166 offset:6144
	v_add_u32_e32 v167, s50, v145
	s_waitcnt lgkmcnt(4)
	s_waitcnt lgkmcnt(3)
	v_mfma_f32_16x16x32_bf16 v[112:115], v[188:191], v[220:223], v[112:115]
	v_mfma_f32_16x16x32_bf16 v[120:123], v[192:195], v[220:223], v[120:123]
	v_mfma_f32_16x16x32_bf16 v[96:99], v[196:199], v[220:223], v[96:99]
	v_mfma_f32_16x16x32_bf16 v[104:107], v[200:203], v[220:223], v[104:107]
	ds_read_b128 v[220:223], v166 offset:8192
	ds_read_b128 v[204:207], v167
	s_waitcnt lgkmcnt(4)
	v_mfma_f32_16x16x32_bf16 v[116:119], v[188:191], v[224:227], v[116:119]
	v_mfma_f32_16x16x32_bf16 v[124:127], v[192:195], v[224:227], v[124:127]
	v_mfma_f32_16x16x32_bf16 v[100:103], v[196:199], v[224:227], v[100:103]
	v_mfma_f32_16x16x32_bf16 v[108:111], v[200:203], v[224:227], v[108:111]
	ds_read_b128 v[224:227], v166 offset:10240
	ds_read_b128 v[208:211], v167 offset:2048
	s_waitcnt lgkmcnt(5)
	v_mfma_f32_16x16x32_bf16 v[80:83], v[188:191], v[228:231], v[80:83]
	v_mfma_f32_16x16x32_bf16 v[88:91], v[192:195], v[228:231], v[88:91]
	v_mfma_f32_16x16x32_bf16 v[64:67], v[196:199], v[228:231], v[64:67]
	v_mfma_f32_16x16x32_bf16 v[72:75], v[200:203], v[228:231], v[72:75]
	ds_read_b128 v[228:231], v166 offset:12288
	ds_read_b128 v[212:215], v167 offset:4096
	s_waitcnt lgkmcnt(6)
	v_mfma_f32_16x16x32_bf16 v[84:87], v[188:191], v[232:235], v[84:87]
	v_mfma_f32_16x16x32_bf16 v[92:95], v[192:195], v[232:235], v[92:95]
	v_mfma_f32_16x16x32_bf16 v[68:71], v[196:199], v[232:235], v[68:71]
	v_mfma_f32_16x16x32_bf16 v[76:79], v[200:203], v[232:235], v[76:79]
	ds_read_b128 v[232:235], v166 offset:14336
	ds_read_b128 v[216:219], v167 offset:6144
	v_add_u32_e32 v166, s49, v143
	s_waitcnt lgkmcnt(7)
	v_mfma_f32_16x16x32_bf16 v[48:51], v[188:191], v[220:223], v[48:51]
	v_mfma_f32_16x16x32_bf16 v[56:59], v[192:195], v[220:223], v[56:59]
	v_mfma_f32_16x16x32_bf16 v[32:35], v[196:199], v[220:223], v[32:35]
	v_mfma_f32_16x16x32_bf16 v[40:43], v[200:203], v[220:223], v[40:43]
	ds_read_b128 v[220:223], v166
	s_waitcnt lgkmcnt(6)
	v_mfma_f32_16x16x32_bf16 v[52:55], v[188:191], v[224:227], v[52:55]
	v_mfma_f32_16x16x32_bf16 v[60:63], v[192:195], v[224:227], v[60:63]
	v_mfma_f32_16x16x32_bf16 v[36:39], v[196:199], v[224:227], v[36:39]
	v_mfma_f32_16x16x32_bf16 v[44:47], v[200:203], v[224:227], v[44:47]
	ds_read_b128 v[224:227], v166 offset:2048
	s_waitcnt lgkmcnt(5)
	v_mfma_f32_16x16x32_bf16 v[16:19], v[188:191], v[228:231], v[16:19]
	v_mfma_f32_16x16x32_bf16 v[24:27], v[192:195], v[228:231], v[24:27]
	v_mfma_f32_16x16x32_bf16 v[0:3], v[196:199], v[228:231], v[0:3]
	v_mfma_f32_16x16x32_bf16 v[8:11], v[200:203], v[228:231], v[8:11]
	ds_read_b128 v[228:231], v166 offset:4096
	s_waitcnt lgkmcnt(4)
	v_mfma_f32_16x16x32_bf16 v[20:23], v[188:191], v[232:235], v[20:23]
	v_mfma_f32_16x16x32_bf16 v[28:31], v[192:195], v[232:235], v[28:31]
	v_mfma_f32_16x16x32_bf16 v[4:7], v[196:199], v[232:235], v[4:7]
	v_mfma_f32_16x16x32_bf16 v[12:15], v[200:203], v[232:235], v[12:15]
	ds_read_b128 v[232:235], v166 offset:6144
	s_waitcnt lgkmcnt(4)
	s_waitcnt lgkmcnt(3)
	v_mfma_f32_16x16x32_bf16 v[112:115], v[204:207], v[220:223], v[112:115]
	v_mfma_f32_16x16x32_bf16 v[120:123], v[208:211], v[220:223], v[120:123]
	v_mfma_f32_16x16x32_bf16 v[96:99], v[212:215], v[220:223], v[96:99]
	v_mfma_f32_16x16x32_bf16 v[104:107], v[216:219], v[220:223], v[104:107]
	ds_read_b128 v[220:223], v166 offset:8192
	s_waitcnt lgkmcnt(3)
	v_mfma_f32_16x16x32_bf16 v[116:119], v[204:207], v[224:227], v[116:119]
	v_mfma_f32_16x16x32_bf16 v[124:127], v[208:211], v[224:227], v[124:127]
	v_mfma_f32_16x16x32_bf16 v[100:103], v[212:215], v[224:227], v[100:103]
	v_mfma_f32_16x16x32_bf16 v[108:111], v[216:219], v[224:227], v[108:111]
	ds_read_b128 v[224:227], v166 offset:10240
	s_waitcnt lgkmcnt(3)
	v_mfma_f32_16x16x32_bf16 v[80:83], v[204:207], v[228:231], v[80:83]
	v_mfma_f32_16x16x32_bf16 v[88:91], v[208:211], v[228:231], v[88:91]
	v_mfma_f32_16x16x32_bf16 v[64:67], v[212:215], v[228:231], v[64:67]
	v_mfma_f32_16x16x32_bf16 v[72:75], v[216:219], v[228:231], v[72:75]
	ds_read_b128 v[228:231], v166 offset:12288
	s_waitcnt lgkmcnt(3)
	v_mfma_f32_16x16x32_bf16 v[84:87], v[204:207], v[232:235], v[84:87]
	v_mfma_f32_16x16x32_bf16 v[92:95], v[208:211], v[232:235], v[92:95]
	v_mfma_f32_16x16x32_bf16 v[68:71], v[212:215], v[232:235], v[68:71]
	v_mfma_f32_16x16x32_bf16 v[76:79], v[216:219], v[232:235], v[76:79]
	ds_read_b128 v[232:235], v166 offset:14336
	s_waitcnt lgkmcnt(3)
	v_mfma_f32_16x16x32_bf16 v[48:51], v[204:207], v[220:223], v[48:51]
	v_mfma_f32_16x16x32_bf16 v[56:59], v[208:211], v[220:223], v[56:59]
	v_mfma_f32_16x16x32_bf16 v[32:35], v[212:215], v[220:223], v[32:35]
	v_mfma_f32_16x16x32_bf16 v[40:43], v[216:219], v[220:223], v[40:43]
	s_waitcnt lgkmcnt(2)
	v_mfma_f32_16x16x32_bf16 v[52:55], v[204:207], v[224:227], v[52:55]
	v_mfma_f32_16x16x32_bf16 v[60:63], v[208:211], v[224:227], v[60:63]
	v_mfma_f32_16x16x32_bf16 v[36:39], v[212:215], v[224:227], v[36:39]
	v_mfma_f32_16x16x32_bf16 v[44:47], v[216:219], v[224:227], v[44:47]
	s_waitcnt lgkmcnt(1)
	v_mfma_f32_16x16x32_bf16 v[16:19], v[204:207], v[228:231], v[16:19]
	v_mfma_f32_16x16x32_bf16 v[24:27], v[208:211], v[228:231], v[24:27]
	v_mfma_f32_16x16x32_bf16 v[0:3], v[212:215], v[228:231], v[0:3]
	v_mfma_f32_16x16x32_bf16 v[8:11], v[216:219], v[228:231], v[8:11]
	s_waitcnt lgkmcnt(0)
	s_waitcnt vmcnt(0)
	s_barrier
	v_mfma_f32_16x16x32_bf16 v[20:23], v[204:207], v[232:235], v[20:23]
	v_mfma_f32_16x16x32_bf16 v[28:31], v[208:211], v[232:235], v[28:31]
	v_mfma_f32_16x16x32_bf16 v[4:7], v[212:215], v[232:235], v[4:7]
	v_mfma_f32_16x16x32_bf16 v[12:15], v[216:219], v[232:235], v[12:15]
	s_nop 15
	v_permlane16_swap_b32_e32 v112, v116
	v_permlane16_swap_b32_e32 v113, v117
	v_permlane16_swap_b32_e32 v114, v118
	v_permlane16_swap_b32_e32 v115, v119
	v_permlane16_swap_b32_e32 v120, v124
	v_permlane16_swap_b32_e32 v121, v125
	v_permlane16_swap_b32_e32 v122, v126
	v_permlane16_swap_b32_e32 v123, v127
	v_permlane16_swap_b32_e32 v96, v100
	v_permlane16_swap_b32_e32 v97, v101
	v_permlane16_swap_b32_e32 v98, v102
	v_permlane16_swap_b32_e32 v99, v103
	v_permlane16_swap_b32_e32 v104, v108
	v_permlane16_swap_b32_e32 v105, v109
	v_permlane16_swap_b32_e32 v106, v110
	v_permlane16_swap_b32_e32 v107, v111
	v_permlane16_swap_b32_e32 v80, v84
	v_permlane16_swap_b32_e32 v81, v85
	v_permlane16_swap_b32_e32 v82, v86
	v_permlane16_swap_b32_e32 v83, v87
	v_permlane16_swap_b32_e32 v88, v92
	v_permlane16_swap_b32_e32 v89, v93
	v_permlane16_swap_b32_e32 v90, v94
	v_permlane16_swap_b32_e32 v91, v95
	v_permlane16_swap_b32_e32 v64, v68
	v_permlane16_swap_b32_e32 v65, v69
	v_permlane16_swap_b32_e32 v66, v70
	v_permlane16_swap_b32_e32 v67, v71
	v_permlane16_swap_b32_e32 v72, v76
	v_permlane16_swap_b32_e32 v73, v77
	v_permlane16_swap_b32_e32 v74, v78
	v_permlane16_swap_b32_e32 v75, v79
	v_permlane16_swap_b32_e32 v48, v52
	v_permlane16_swap_b32_e32 v49, v53
	v_permlane16_swap_b32_e32 v50, v54
	v_permlane16_swap_b32_e32 v51, v55
	v_permlane16_swap_b32_e32 v56, v60
	v_permlane16_swap_b32_e32 v57, v61
	v_permlane16_swap_b32_e32 v58, v62
	v_permlane16_swap_b32_e32 v59, v63
	v_permlane16_swap_b32_e32 v32, v36
	v_permlane16_swap_b32_e32 v33, v37
	v_permlane16_swap_b32_e32 v34, v38
	v_permlane16_swap_b32_e32 v35, v39
	v_permlane16_swap_b32_e32 v40, v44
	v_permlane16_swap_b32_e32 v41, v45
	v_permlane16_swap_b32_e32 v42, v46
	v_permlane16_swap_b32_e32 v43, v47
	v_permlane16_swap_b32_e32 v16, v20
	v_permlane16_swap_b32_e32 v17, v21
	v_permlane16_swap_b32_e32 v18, v22
	v_permlane16_swap_b32_e32 v19, v23
	v_permlane16_swap_b32_e32 v24, v28
	v_permlane16_swap_b32_e32 v25, v29
	v_permlane16_swap_b32_e32 v26, v30
	v_permlane16_swap_b32_e32 v27, v31
	v_permlane16_swap_b32_e32 v0, v4
	v_permlane16_swap_b32_e32 v1, v5
	v_permlane16_swap_b32_e32 v2, v6
	v_permlane16_swap_b32_e32 v3, v7
	v_permlane16_swap_b32_e32 v8, v12
	v_permlane16_swap_b32_e32 v9, v13
	v_permlane16_swap_b32_e32 v10, v14
	v_permlane16_swap_b32_e32 v11, v15
	v_permlane32_swap_b32_e32 v112, v116
	v_permlane32_swap_b32_e32 v113, v117
	v_permlane32_swap_b32_e32 v114, v118
	v_permlane32_swap_b32_e32 v115, v119
	v_permlane32_swap_b32_e32 v120, v124
	v_permlane32_swap_b32_e32 v121, v125
	v_permlane32_swap_b32_e32 v122, v126
	v_permlane32_swap_b32_e32 v123, v127
	v_permlane32_swap_b32_e32 v96, v100
	v_permlane32_swap_b32_e32 v97, v101
	v_permlane32_swap_b32_e32 v98, v102
	v_permlane32_swap_b32_e32 v99, v103
	v_permlane32_swap_b32_e32 v104, v108
	v_permlane32_swap_b32_e32 v105, v109
	v_permlane32_swap_b32_e32 v106, v110
	v_permlane32_swap_b32_e32 v107, v111
	v_permlane32_swap_b32_e32 v80, v84
	v_permlane32_swap_b32_e32 v81, v85
	v_permlane32_swap_b32_e32 v82, v86
	v_permlane32_swap_b32_e32 v83, v87
	v_permlane32_swap_b32_e32 v88, v92
	v_permlane32_swap_b32_e32 v89, v93
	v_permlane32_swap_b32_e32 v90, v94
	v_permlane32_swap_b32_e32 v91, v95
	v_permlane32_swap_b32_e32 v64, v68
	v_permlane32_swap_b32_e32 v65, v69
	v_permlane32_swap_b32_e32 v66, v70
	v_permlane32_swap_b32_e32 v67, v71
	v_permlane32_swap_b32_e32 v72, v76
	v_permlane32_swap_b32_e32 v73, v77
	v_permlane32_swap_b32_e32 v74, v78
	v_permlane32_swap_b32_e32 v75, v79
	v_permlane32_swap_b32_e32 v48, v52
	v_permlane32_swap_b32_e32 v49, v53
	v_permlane32_swap_b32_e32 v50, v54
	v_permlane32_swap_b32_e32 v51, v55
	v_permlane32_swap_b32_e32 v56, v60
	v_permlane32_swap_b32_e32 v57, v61
	v_permlane32_swap_b32_e32 v58, v62
	v_permlane32_swap_b32_e32 v59, v63
	v_permlane32_swap_b32_e32 v32, v36
	v_permlane32_swap_b32_e32 v33, v37
	v_permlane32_swap_b32_e32 v34, v38
	v_permlane32_swap_b32_e32 v35, v39
	v_permlane32_swap_b32_e32 v40, v44
	v_permlane32_swap_b32_e32 v41, v45
	v_permlane32_swap_b32_e32 v42, v46
	v_permlane32_swap_b32_e32 v43, v47
	v_permlane32_swap_b32_e32 v16, v20
	v_permlane32_swap_b32_e32 v17, v21
	v_permlane32_swap_b32_e32 v18, v22
	v_permlane32_swap_b32_e32 v19, v23
	v_permlane32_swap_b32_e32 v24, v28
	v_permlane32_swap_b32_e32 v25, v29
	v_permlane32_swap_b32_e32 v26, v30
	v_permlane32_swap_b32_e32 v27, v31
	v_permlane32_swap_b32_e32 v0, v4
	v_permlane32_swap_b32_e32 v1, v5
	v_permlane32_swap_b32_e32 v2, v6
	v_permlane32_swap_b32_e32 v3, v7
	v_permlane32_swap_b32_e32 v8, v12
	v_permlane32_swap_b32_e32 v9, v13
	v_permlane32_swap_b32_e32 v10, v14
	v_permlane32_swap_b32_e32 v11, v15
	s_nop 1
	s_branch .LBB0_163

.Lg163_loop:
	s_add_u32 s51, s50, 0x10000
	s_sub_u32 s53, s51, 0x28000
	s_cmp_ge_u32 s51, 0x28000
	s_cselect_b32 s51, s53, s51
	s_add_u32 s52, s49, 0x20000
	s_sub_u32 s53, s52, 0x28000
	s_cmp_ge_u32 s52, 0x28000
	s_cselect_b32 s52, s53, s52
	v_add_u32_e32 v246, s50, v244
	s_waitcnt lgkmcnt(4)
	s_waitcnt lgkmcnt(3)
	v_mfma_f32_16x16x32_bf16 v[112:115], v[192:195], v[224:227], v[112:115]
	v_mfma_f32_16x16x32_bf16 v[120:123], v[196:199], v[224:227], v[120:123]
	v_mfma_f32_16x16x32_bf16 v[96:99], v[200:203], v[224:227], v[96:99]
	v_mfma_f32_16x16x32_bf16 v[104:107], v[204:207], v[224:227], v[104:107]
	s_add_u32 m0, s51, s48
	s_nop 0
	global_load_lds_dwordx4 v248, s[64:65]
	s_add_u32 s64, s64, 0x80
	s_addc_u32 s65, s65, 0
	s_add_u32 s53, s51, s48
	s_add_u32 m0, s53, 0x2000
	s_nop 0
	global_load_lds_dwordx4 v248, s[66:67]
	s_add_u32 s66, s66, 0x80
	s_addc_u32 s67, s67, 0
	ds_read_b128 v[224:227], v245 offset:8192
	ds_read_b128 v[208:211], v246
	s_waitcnt lgkmcnt(4)
	v_mfma_f32_16x16x32_bf16 v[116:119], v[192:195], v[228:231], v[116:119]
	v_mfma_f32_16x16x32_bf16 v[124:127], v[196:199], v[228:231], v[124:127]
	v_mfma_f32_16x16x32_bf16 v[100:103], v[200:203], v[228:231], v[100:103]
	v_mfma_f32_16x16x32_bf16 v[108:111], v[204:207], v[228:231], v[108:111]
	s_add_u32 s53, s51, s48
	s_add_u32 m0, s53, 0x4000
	s_nop 0
	global_load_lds_dwordx4 v248, s[68:69]
	s_add_u32 s68, s68, 0x80
	s_addc_u32 s69, s69, 0
	s_add_u32 s53, s51, s48
	s_add_u32 m0, s53, 0x6000
	s_nop 0
	global_load_lds_dwordx4 v248, s[70:71]
	s_add_u32 s70, s70, 0x80
	s_addc_u32 s71, s71, 0
	ds_read_b128 v[228:231], v245 offset:10240
	ds_read_b128 v[212:215], v246 offset:2048
	s_waitcnt lgkmcnt(5)
	v_mfma_f32_16x16x32_bf16 v[80:83], v[192:195], v[232:235], v[80:83]
	v_mfma_f32_16x16x32_bf16 v[88:91], v[196:199], v[232:235], v[88:91]
	v_mfma_f32_16x16x32_bf16 v[64:67], v[200:203], v[232:235], v[64:67]
	v_mfma_f32_16x16x32_bf16 v[72:75], v[204:207], v[232:235], v[72:75]
	s_add_u32 m0, s52, s48
	s_nop 0
	global_load_lds_dwordx4 v247, s[56:57]
	s_add_u32 s56, s56, 0x80
	s_addc_u32 s57, s57, 0
	s_add_u32 s53, s52, s48
	s_add_u32 m0, s53, 0x2000
	s_nop 0
	global_load_lds_dwordx4 v247, s[58:59]
	s_add_u32 s58, s58, 0x80
	s_addc_u32 s59, s59, 0
	ds_read_b128 v[232:235], v245 offset:12288
	ds_read_b128 v[216:219], v246 offset:4096
	s_waitcnt lgkmcnt(6)
	v_mfma_f32_16x16x32_bf16 v[84:87], v[192:195], v[236:239], v[84:87]
	v_mfma_f32_16x16x32_bf16 v[92:95], v[196:199], v[236:239], v[92:95]
	v_mfma_f32_16x16x32_bf16 v[68:71], v[200:203], v[236:239], v[68:71]
	v_mfma_f32_16x16x32_bf16 v[76:79], v[204:207], v[236:239], v[76:79]
	s_add_u32 s53, s52, s48
	s_add_u32 m0, s53, 0x4000
	s_nop 0
	global_load_lds_dwordx4 v247, s[60:61]
	s_add_u32 s60, s60, 0x80
	s_addc_u32 s61, s61, 0
	s_add_u32 s53, s52, s48
	s_add_u32 m0, s53, 0x6000
	s_nop 0
	global_load_lds_dwordx4 v247, s[62:63]
	s_add_u32 s62, s62, 0x80
	s_addc_u32 s63, s63, 0
	ds_read_b128 v[236:239], v245 offset:14336
	ds_read_b128 v[220:223], v246 offset:6144
	v_add_u32_e32 v245, s49, v241
	s_waitcnt lgkmcnt(7)
	v_mfma_f32_16x16x32_bf16 v[48:51], v[192:195], v[224:227], v[48:51]
	v_mfma_f32_16x16x32_bf16 v[56:59], v[196:199], v[224:227], v[56:59]
	v_mfma_f32_16x16x32_bf16 v[32:35], v[200:203], v[224:227], v[32:35]
	v_mfma_f32_16x16x32_bf16 v[40:43], v[204:207], v[224:227], v[40:43]
	ds_read_b128 v[224:227], v245
	s_waitcnt lgkmcnt(6)
	v_mfma_f32_16x16x32_bf16 v[52:55], v[192:195], v[228:231], v[52:55]
	v_mfma_f32_16x16x32_bf16 v[60:63], v[196:199], v[228:231], v[60:63]
	v_mfma_f32_16x16x32_bf16 v[36:39], v[200:203], v[228:231], v[36:39]
	v_mfma_f32_16x16x32_bf16 v[44:47], v[204:207], v[228:231], v[44:47]
	ds_read_b128 v[228:231], v245 offset:2048
	s_waitcnt lgkmcnt(5)
	v_mfma_f32_16x16x32_bf16 v[16:19], v[192:195], v[232:235], v[16:19]
	v_mfma_f32_16x16x32_bf16 v[24:27], v[196:199], v[232:235], v[24:27]
	v_mfma_f32_16x16x32_bf16 v[0:3], v[200:203], v[232:235], v[0:3]
	v_mfma_f32_16x16x32_bf16 v[8:11], v[204:207], v[232:235], v[8:11]
	ds_read_b128 v[232:235], v245 offset:4096
	s_waitcnt lgkmcnt(4)
	v_mfma_f32_16x16x32_bf16 v[20:23], v[192:195], v[236:239], v[20:23]
	v_mfma_f32_16x16x32_bf16 v[28:31], v[196:199], v[236:239], v[28:31]
	v_mfma_f32_16x16x32_bf16 v[4:7], v[200:203], v[236:239], v[4:7]
	v_mfma_f32_16x16x32_bf16 v[12:15], v[204:207], v[236:239], v[12:15]
	ds_read_b128 v[236:239], v245 offset:6144
	s_waitcnt lgkmcnt(4)
	s_waitcnt lgkmcnt(3)
	v_mfma_f32_16x16x32_bf16 v[112:115], v[208:211], v[224:227], v[112:115]
	v_mfma_f32_16x16x32_bf16 v[120:123], v[212:215], v[224:227], v[120:123]
	v_mfma_f32_16x16x32_bf16 v[96:99], v[216:219], v[224:227], v[96:99]
	v_mfma_f32_16x16x32_bf16 v[104:107], v[220:223], v[224:227], v[104:107]
	ds_read_b128 v[224:227], v245 offset:8192
	s_waitcnt lgkmcnt(3)
	v_mfma_f32_16x16x32_bf16 v[116:119], v[208:211], v[228:231], v[116:119]
	v_mfma_f32_16x16x32_bf16 v[124:127], v[212:215], v[228:231], v[124:127]
	v_mfma_f32_16x16x32_bf16 v[100:103], v[216:219], v[228:231], v[100:103]
	v_mfma_f32_16x16x32_bf16 v[108:111], v[220:223], v[228:231], v[108:111]
	ds_read_b128 v[228:231], v245 offset:10240
	s_waitcnt lgkmcnt(3)
	v_mfma_f32_16x16x32_bf16 v[80:83], v[208:211], v[232:235], v[80:83]
	v_mfma_f32_16x16x32_bf16 v[88:91], v[212:215], v[232:235], v[88:91]
	v_mfma_f32_16x16x32_bf16 v[64:67], v[216:219], v[232:235], v[64:67]
	v_mfma_f32_16x16x32_bf16 v[72:75], v[220:223], v[232:235], v[72:75]
	ds_read_b128 v[232:235], v245 offset:12288
	s_waitcnt lgkmcnt(3)
	v_mfma_f32_16x16x32_bf16 v[84:87], v[208:211], v[236:239], v[84:87]
	v_mfma_f32_16x16x32_bf16 v[92:95], v[212:215], v[236:239], v[92:95]
	v_mfma_f32_16x16x32_bf16 v[68:71], v[216:219], v[236:239], v[68:71]
	v_mfma_f32_16x16x32_bf16 v[76:79], v[220:223], v[236:239], v[76:79]
	ds_read_b128 v[236:239], v245 offset:14336
	s_waitcnt lgkmcnt(3)
	v_mfma_f32_16x16x32_bf16 v[48:51], v[208:211], v[224:227], v[48:51]
	v_mfma_f32_16x16x32_bf16 v[56:59], v[212:215], v[224:227], v[56:59]
	v_mfma_f32_16x16x32_bf16 v[32:35], v[216:219], v[224:227], v[32:35]
	v_mfma_f32_16x16x32_bf16 v[40:43], v[220:223], v[224:227], v[40:43]
	s_waitcnt lgkmcnt(2)
	v_mfma_f32_16x16x32_bf16 v[52:55], v[208:211], v[228:231], v[52:55]
	v_mfma_f32_16x16x32_bf16 v[60:63], v[212:215], v[228:231], v[60:63]
	v_mfma_f32_16x16x32_bf16 v[36:39], v[216:219], v[228:231], v[36:39]
	v_mfma_f32_16x16x32_bf16 v[44:47], v[220:223], v[228:231], v[44:47]
	s_waitcnt lgkmcnt(1)
	v_mfma_f32_16x16x32_bf16 v[16:19], v[208:211], v[232:235], v[16:19]
	v_mfma_f32_16x16x32_bf16 v[24:27], v[212:215], v[232:235], v[24:27]
	v_mfma_f32_16x16x32_bf16 v[0:3], v[216:219], v[232:235], v[0:3]
	v_mfma_f32_16x16x32_bf16 v[8:11], v[220:223], v[232:235], v[8:11]
	s_waitcnt lgkmcnt(0)
	s_add_u32 s28, s28, 0x80
	s_addc_u32 s29, s29, 0
	s_add_u32 s49, s49, 0x10000
	s_sub_u32 s53, s49, 0x28000
	s_cmp_ge_u32 s49, 0x28000
	s_cselect_b32 s49, s53, s49
	s_mov_b32 s50, s51
	s_waitcnt vmcnt(4)
	s_barrier
	v_add_u32_e32 v246, s50, v243
	v_add_u32_e32 v245, s49, v240
	ds_read_b128 v[192:195], v246
	ds_read_b128 v[196:199], v246 offset:2048
	ds_read_b128 v[200:203], v246 offset:4096
	ds_read_b128 v[204:207], v246 offset:6144
	ds_read_b128 v[224:227], v245
	ds_read_b128 v[228:231], v245 offset:2048
	ds_read_b128 v[232:235], v245 offset:4096
	v_mfma_f32_16x16x32_bf16 v[20:23], v[208:211], v[236:239], v[20:23]
	v_mfma_f32_16x16x32_bf16 v[28:31], v[212:215], v[236:239], v[28:31]
	v_mfma_f32_16x16x32_bf16 v[4:7], v[216:219], v[236:239], v[4:7]
	v_mfma_f32_16x16x32_bf16 v[12:15], v[220:223], v[236:239], v[12:15]
	ds_read_b128 v[236:239], v245 offset:6144
	s_cmpk_lg_i32 s28, 0xf00
	s_cbranch_scc1 .Lg163_loop
	s_add_u32 s51, s50, 0x10000
	s_sub_u32 s53, s51, 0x28000
	s_cmp_ge_u32 s51, 0x28000
	s_cselect_b32 s51, s53, s51
	v_add_u32_e32 v246, s50, v244
	s_waitcnt lgkmcnt(4)
	s_waitcnt lgkmcnt(3)
	v_mfma_f32_16x16x32_bf16 v[112:115], v[192:195], v[224:227], v[112:115]
	v_mfma_f32_16x16x32_bf16 v[120:123], v[196:199], v[224:227], v[120:123]
	v_mfma_f32_16x16x32_bf16 v[96:99], v[200:203], v[224:227], v[96:99]
	v_mfma_f32_16x16x32_bf16 v[104:107], v[204:207], v[224:227], v[104:107]
	s_add_u32 m0, s51, s48
	s_nop 0
	global_load_lds_dwordx4 v248, s[64:65]
	s_add_u32 s64, s64, 0x80
	s_addc_u32 s65, s65, 0
	s_add_u32 s53, s51, s48
	s_add_u32 m0, s53, 0x2000
	s_nop 0
	global_load_lds_dwordx4 v248, s[66:67]
	s_add_u32 s66, s66, 0x80
	s_addc_u32 s67, s67, 0
	ds_read_b128 v[224:227], v245 offset:8192
	ds_read_b128 v[208:211], v246
	s_waitcnt lgkmcnt(4)
	v_mfma_f32_16x16x32_bf16 v[116:119], v[192:195], v[228:231], v[116:119]
	v_mfma_f32_16x16x32_bf16 v[124:127], v[196:199], v[228:231], v[124:127]
	v_mfma_f32_16x16x32_bf16 v[100:103], v[200:203], v[228:231], v[100:103]
	v_mfma_f32_16x16x32_bf16 v[108:111], v[204:207], v[228:231], v[108:111]
	s_add_u32 s53, s51, s48
	s_add_u32 m0, s53, 0x4000
	s_nop 0
	global_load_lds_dwordx4 v248, s[68:69]
	s_add_u32 s68, s68, 0x80
	s_addc_u32 s69, s69, 0
	s_add_u32 s53, s51, s48
	s_add_u32 m0, s53, 0x6000
	s_nop 0
	global_load_lds_dwordx4 v248, s[70:71]
	s_add_u32 s70, s70, 0x80
	s_addc_u32 s71, s71, 0
	ds_read_b128 v[228:231], v245 offset:10240
	ds_read_b128 v[212:215], v246 offset:2048
	s_waitcnt lgkmcnt(5)
	v_mfma_f32_16x16x32_bf16 v[80:83], v[192:195], v[232:235], v[80:83]
	v_mfma_f32_16x16x32_bf16 v[88:91], v[196:199], v[232:235], v[88:91]
	v_mfma_f32_16x16x32_bf16 v[64:67], v[200:203], v[232:235], v[64:67]
	v_mfma_f32_16x16x32_bf16 v[72:75], v[204:207], v[232:235], v[72:75]
	ds_read_b128 v[232:235], v245 offset:12288
	ds_read_b128 v[216:219], v246 offset:4096
	s_waitcnt lgkmcnt(6)
	v_mfma_f32_16x16x32_bf16 v[84:87], v[192:195], v[236:239], v[84:87]
	v_mfma_f32_16x16x32_bf16 v[92:95], v[196:199], v[236:239], v[92:95]
	v_mfma_f32_16x16x32_bf16 v[68:71], v[200:203], v[236:239], v[68:71]
	v_mfma_f32_16x16x32_bf16 v[76:79], v[204:207], v[236:239], v[76:79]
	ds_read_b128 v[236:239], v245 offset:14336
	ds_read_b128 v[220:223], v246 offset:6144
	v_add_u32_e32 v245, s49, v241
	s_waitcnt lgkmcnt(7)
	v_mfma_f32_16x16x32_bf16 v[48:51], v[192:195], v[224:227], v[48:51]
	v_mfma_f32_16x16x32_bf16 v[56:59], v[196:199], v[224:227], v[56:59]
	v_mfma_f32_16x16x32_bf16 v[32:35], v[200:203], v[224:227], v[32:35]
	v_mfma_f32_16x16x32_bf16 v[40:43], v[204:207], v[224:227], v[40:43]
	ds_read_b128 v[224:227], v245
	s_waitcnt lgkmcnt(6)
	v_mfma_f32_16x16x32_bf16 v[52:55], v[192:195], v[228:231], v[52:55]
	v_mfma_f32_16x16x32_bf16 v[60:63], v[196:199], v[228:231], v[60:63]
	v_mfma_f32_16x16x32_bf16 v[36:39], v[200:203], v[228:231], v[36:39]
	v_mfma_f32_16x16x32_bf16 v[44:47], v[204:207], v[228:231], v[44:47]
	ds_read_b128 v[228:231], v245 offset:2048
	s_waitcnt lgkmcnt(5)
	v_mfma_f32_16x16x32_bf16 v[16:19], v[192:195], v[232:235], v[16:19]
	v_mfma_f32_16x16x32_bf16 v[24:27], v[196:199], v[232:235], v[24:27]
	v_mfma_f32_16x16x32_bf16 v[0:3], v[200:203], v[232:235], v[0:3]
	v_mfma_f32_16x16x32_bf16 v[8:11], v[204:207], v[232:235], v[8:11]
	ds_read_b128 v[232:235], v245 offset:4096
	s_waitcnt lgkmcnt(4)
	v_mfma_f32_16x16x32_bf16 v[20:23], v[192:195], v[236:239], v[20:23]
	v_mfma_f32_16x16x32_bf16 v[28:31], v[196:199], v[236:239], v[28:31]
	v_mfma_f32_16x16x32_bf16 v[4:7], v[200:203], v[236:239], v[4:7]
	v_mfma_f32_16x16x32_bf16 v[12:15], v[204:207], v[236:239], v[12:15]
	ds_read_b128 v[236:239], v245 offset:6144
	s_waitcnt lgkmcnt(4)
	s_waitcnt lgkmcnt(3)
	v_mfma_f32_16x16x32_bf16 v[112:115], v[208:211], v[224:227], v[112:115]
	v_mfma_f32_16x16x32_bf16 v[120:123], v[212:215], v[224:227], v[120:123]
	v_mfma_f32_16x16x32_bf16 v[96:99], v[216:219], v[224:227], v[96:99]
	v_mfma_f32_16x16x32_bf16 v[104:107], v[220:223], v[224:227], v[104:107]
	ds_read_b128 v[224:227], v245 offset:8192
	s_waitcnt lgkmcnt(3)
	v_mfma_f32_16x16x32_bf16 v[116:119], v[208:211], v[228:231], v[116:119]
	v_mfma_f32_16x16x32_bf16 v[124:127], v[212:215], v[228:231], v[124:127]
	v_mfma_f32_16x16x32_bf16 v[100:103], v[216:219], v[228:231], v[100:103]
	v_mfma_f32_16x16x32_bf16 v[108:111], v[220:223], v[228:231], v[108:111]
	ds_read_b128 v[228:231], v245 offset:10240
	s_waitcnt lgkmcnt(3)
	v_mfma_f32_16x16x32_bf16 v[80:83], v[208:211], v[232:235], v[80:83]
	v_mfma_f32_16x16x32_bf16 v[88:91], v[212:215], v[232:235], v[88:91]
	v_mfma_f32_16x16x32_bf16 v[64:67], v[216:219], v[232:235], v[64:67]
	v_mfma_f32_16x16x32_bf16 v[72:75], v[220:223], v[232:235], v[72:75]
	ds_read_b128 v[232:235], v245 offset:12288
	s_waitcnt lgkmcnt(3)
	v_mfma_f32_16x16x32_bf16 v[84:87], v[208:211], v[236:239], v[84:87]
	v_mfma_f32_16x16x32_bf16 v[92:95], v[212:215], v[236:239], v[92:95]
	v_mfma_f32_16x16x32_bf16 v[68:71], v[216:219], v[236:239], v[68:71]
	v_mfma_f32_16x16x32_bf16 v[76:79], v[220:223], v[236:239], v[76:79]
	ds_read_b128 v[236:239], v245 offset:14336
	s_waitcnt lgkmcnt(3)
	v_mfma_f32_16x16x32_bf16 v[48:51], v[208:211], v[224:227], v[48:51]
	v_mfma_f32_16x16x32_bf16 v[56:59], v[212:215], v[224:227], v[56:59]
	v_mfma_f32_16x16x32_bf16 v[32:35], v[216:219], v[224:227], v[32:35]
	v_mfma_f32_16x16x32_bf16 v[40:43], v[220:223], v[224:227], v[40:43]
	s_waitcnt lgkmcnt(2)
	v_mfma_f32_16x16x32_bf16 v[52:55], v[208:211], v[228:231], v[52:55]
	v_mfma_f32_16x16x32_bf16 v[60:63], v[212:215], v[228:231], v[60:63]
	v_mfma_f32_16x16x32_bf16 v[36:39], v[216:219], v[228:231], v[36:39]
	v_mfma_f32_16x16x32_bf16 v[44:47], v[220:223], v[228:231], v[44:47]
	s_waitcnt lgkmcnt(1)
	v_mfma_f32_16x16x32_bf16 v[16:19], v[208:211], v[232:235], v[16:19]
	v_mfma_f32_16x16x32_bf16 v[24:27], v[212:215], v[232:235], v[24:27]
	v_mfma_f32_16x16x32_bf16 v[0:3], v[216:219], v[232:235], v[0:3]
	v_mfma_f32_16x16x32_bf16 v[8:11], v[220:223], v[232:235], v[8:11]
	s_waitcnt lgkmcnt(0)
	s_add_u32 s28, s28, 0x80
	s_addc_u32 s29, s29, 0
	s_add_u32 s49, s49, 0x10000
	s_sub_u32 s53, s49, 0x28000
	s_cmp_ge_u32 s49, 0x28000
	s_cselect_b32 s49, s53, s49
	s_mov_b32 s50, s51
	s_waitcnt vmcnt(0)
	s_barrier
	v_add_u32_e32 v246, s50, v243
	v_add_u32_e32 v245, s49, v240
	ds_read_b128 v[192:195], v246
	ds_read_b128 v[196:199], v246 offset:2048
	ds_read_b128 v[200:203], v246 offset:4096
	ds_read_b128 v[204:207], v246 offset:6144
	ds_read_b128 v[224:227], v245
	ds_read_b128 v[228:231], v245 offset:2048
	ds_read_b128 v[232:235], v245 offset:4096
	v_mfma_f32_16x16x32_bf16 v[20:23], v[208:211], v[236:239], v[20:23]
	v_mfma_f32_16x16x32_bf16 v[28:31], v[212:215], v[236:239], v[28:31]
	v_mfma_f32_16x16x32_bf16 v[4:7], v[216:219], v[236:239], v[4:7]
	v_mfma_f32_16x16x32_bf16 v[12:15], v[220:223], v[236:239], v[12:15]
	ds_read_b128 v[236:239], v245 offset:6144
	v_add_u32_e32 v246, s50, v244
	s_waitcnt lgkmcnt(4)
	s_waitcnt lgkmcnt(3)
	v_mfma_f32_16x16x32_bf16 v[112:115], v[192:195], v[224:227], v[112:115]
	v_mfma_f32_16x16x32_bf16 v[120:123], v[196:199], v[224:227], v[120:123]
	v_mfma_f32_16x16x32_bf16 v[96:99], v[200:203], v[224:227], v[96:99]
	v_mfma_f32_16x16x32_bf16 v[104:107], v[204:207], v[224:227], v[104:107]
	ds_read_b128 v[224:227], v245 offset:8192
	ds_read_b128 v[208:211], v246
	s_waitcnt lgkmcnt(4)
	v_mfma_f32_16x16x32_bf16 v[116:119], v[192:195], v[228:231], v[116:119]
	v_mfma_f32_16x16x32_bf16 v[124:127], v[196:199], v[228:231], v[124:127]
	v_mfma_f32_16x16x32_bf16 v[100:103], v[200:203], v[228:231], v[100:103]
	v_mfma_f32_16x16x32_bf16 v[108:111], v[204:207], v[228:231], v[108:111]
	ds_read_b128 v[228:231], v245 offset:10240
	ds_read_b128 v[212:215], v246 offset:2048
	s_waitcnt lgkmcnt(5)
	v_mfma_f32_16x16x32_bf16 v[80:83], v[192:195], v[232:235], v[80:83]
	v_mfma_f32_16x16x32_bf16 v[88:91], v[196:199], v[232:235], v[88:91]
	v_mfma_f32_16x16x32_bf16 v[64:67], v[200:203], v[232:235], v[64:67]
	v_mfma_f32_16x16x32_bf16 v[72:75], v[204:207], v[232:235], v[72:75]
	ds_read_b128 v[232:235], v245 offset:12288
	ds_read_b128 v[216:219], v246 offset:4096
	s_waitcnt lgkmcnt(6)
	v_mfma_f32_16x16x32_bf16 v[84:87], v[192:195], v[236:239], v[84:87]
	v_mfma_f32_16x16x32_bf16 v[92:95], v[196:199], v[236:239], v[92:95]
	v_mfma_f32_16x16x32_bf16 v[68:71], v[200:203], v[236:239], v[68:71]
	v_mfma_f32_16x16x32_bf16 v[76:79], v[204:207], v[236:239], v[76:79]
	ds_read_b128 v[236:239], v245 offset:14336
	ds_read_b128 v[220:223], v246 offset:6144
	v_add_u32_e32 v245, s49, v241
	s_waitcnt lgkmcnt(7)
	v_mfma_f32_16x16x32_bf16 v[48:51], v[192:195], v[224:227], v[48:51]
	v_mfma_f32_16x16x32_bf16 v[56:59], v[196:199], v[224:227], v[56:59]
	v_mfma_f32_16x16x32_bf16 v[32:35], v[200:203], v[224:227], v[32:35]
	v_mfma_f32_16x16x32_bf16 v[40:43], v[204:207], v[224:227], v[40:43]
	ds_read_b128 v[224:227], v245
	s_waitcnt lgkmcnt(6)
	v_mfma_f32_16x16x32_bf16 v[52:55], v[192:195], v[228:231], v[52:55]
	v_mfma_f32_16x16x32_bf16 v[60:63], v[196:199], v[228:231], v[60:63]
	v_mfma_f32_16x16x32_bf16 v[36:39], v[200:203], v[228:231], v[36:39]
	v_mfma_f32_16x16x32_bf16 v[44:47], v[204:207], v[228:231], v[44:47]
	ds_read_b128 v[228:231], v245 offset:2048
	s_waitcnt lgkmcnt(5)
	v_mfma_f32_16x16x32_bf16 v[16:19], v[192:195], v[232:235], v[16:19]
	v_mfma_f32_16x16x32_bf16 v[24:27], v[196:199], v[232:235], v[24:27]
	v_mfma_f32_16x16x32_bf16 v[0:3], v[200:203], v[232:235], v[0:3]
	v_mfma_f32_16x16x32_bf16 v[8:11], v[204:207], v[232:235], v[8:11]
	ds_read_b128 v[232:235], v245 offset:4096
	s_waitcnt lgkmcnt(4)
	v_mfma_f32_16x16x32_bf16 v[20:23], v[192:195], v[236:239], v[20:23]
	v_mfma_f32_16x16x32_bf16 v[28:31], v[196:199], v[236:239], v[28:31]
	v_mfma_f32_16x16x32_bf16 v[4:7], v[200:203], v[236:239], v[4:7]
	v_mfma_f32_16x16x32_bf16 v[12:15], v[204:207], v[236:239], v[12:15]
	ds_read_b128 v[236:239], v245 offset:6144
	s_waitcnt lgkmcnt(4)
	s_waitcnt lgkmcnt(3)
	v_mfma_f32_16x16x32_bf16 v[112:115], v[208:211], v[224:227], v[112:115]
	v_mfma_f32_16x16x32_bf16 v[120:123], v[212:215], v[224:227], v[120:123]
	v_mfma_f32_16x16x32_bf16 v[96:99], v[216:219], v[224:227], v[96:99]
	v_mfma_f32_16x16x32_bf16 v[104:107], v[220:223], v[224:227], v[104:107]
	ds_read_b128 v[224:227], v245 offset:8192
	s_waitcnt lgkmcnt(3)
	v_mfma_f32_16x16x32_bf16 v[116:119], v[208:211], v[228:231], v[116:119]
	v_mfma_f32_16x16x32_bf16 v[124:127], v[212:215], v[228:231], v[124:127]
	v_mfma_f32_16x16x32_bf16 v[100:103], v[216:219], v[228:231], v[100:103]
	v_mfma_f32_16x16x32_bf16 v[108:111], v[220:223], v[228:231], v[108:111]
	ds_read_b128 v[228:231], v245 offset:10240
	s_waitcnt lgkmcnt(3)
	v_mfma_f32_16x16x32_bf16 v[80:83], v[208:211], v[232:235], v[80:83]
	v_mfma_f32_16x16x32_bf16 v[88:91], v[212:215], v[232:235], v[88:91]
	v_mfma_f32_16x16x32_bf16 v[64:67], v[216:219], v[232:235], v[64:67]
	v_mfma_f32_16x16x32_bf16 v[72:75], v[220:223], v[232:235], v[72:75]
	ds_read_b128 v[232:235], v245 offset:12288
	s_waitcnt lgkmcnt(3)
	v_mfma_f32_16x16x32_bf16 v[84:87], v[208:211], v[236:239], v[84:87]
	v_mfma_f32_16x16x32_bf16 v[92:95], v[212:215], v[236:239], v[92:95]
	v_mfma_f32_16x16x32_bf16 v[68:71], v[216:219], v[236:239], v[68:71]
	v_mfma_f32_16x16x32_bf16 v[76:79], v[220:223], v[236:239], v[76:79]
	ds_read_b128 v[236:239], v245 offset:14336
	s_waitcnt lgkmcnt(3)
	v_mfma_f32_16x16x32_bf16 v[48:51], v[208:211], v[224:227], v[48:51]
	v_mfma_f32_16x16x32_bf16 v[56:59], v[212:215], v[224:227], v[56:59]
	v_mfma_f32_16x16x32_bf16 v[32:35], v[216:219], v[224:227], v[32:35]
	v_mfma_f32_16x16x32_bf16 v[40:43], v[220:223], v[224:227], v[40:43]
	s_waitcnt lgkmcnt(2)
	v_mfma_f32_16x16x32_bf16 v[52:55], v[208:211], v[228:231], v[52:55]
	v_mfma_f32_16x16x32_bf16 v[60:63], v[212:215], v[228:231], v[60:63]
	v_mfma_f32_16x16x32_bf16 v[36:39], v[216:219], v[228:231], v[36:39]
	v_mfma_f32_16x16x32_bf16 v[44:47], v[220:223], v[228:231], v[44:47]
	s_waitcnt lgkmcnt(1)
	v_mfma_f32_16x16x32_bf16 v[16:19], v[208:211], v[232:235], v[16:19]
	v_mfma_f32_16x16x32_bf16 v[24:27], v[212:215], v[232:235], v[24:27]
	v_mfma_f32_16x16x32_bf16 v[0:3], v[216:219], v[232:235], v[0:3]
	v_mfma_f32_16x16x32_bf16 v[8:11], v[220:223], v[232:235], v[8:11]
	s_waitcnt lgkmcnt(0)
	s_waitcnt vmcnt(0)
	s_barrier
	v_mfma_f32_16x16x32_bf16 v[20:23], v[208:211], v[236:239], v[20:23]
	v_mfma_f32_16x16x32_bf16 v[28:31], v[212:215], v[236:239], v[28:31]
	v_mfma_f32_16x16x32_bf16 v[4:7], v[216:219], v[236:239], v[4:7]
	v_mfma_f32_16x16x32_bf16 v[12:15], v[220:223], v[236:239], v[12:15]
	s_nop 15
	v_permlane16_swap_b32_e32 v112, v116
	v_permlane16_swap_b32_e32 v113, v117
	v_permlane16_swap_b32_e32 v114, v118
	v_permlane16_swap_b32_e32 v115, v119
	v_permlane16_swap_b32_e32 v120, v124
	v_permlane16_swap_b32_e32 v121, v125
	v_permlane16_swap_b32_e32 v122, v126
	v_permlane16_swap_b32_e32 v123, v127
	v_permlane16_swap_b32_e32 v96, v100
	v_permlane16_swap_b32_e32 v97, v101
	v_permlane16_swap_b32_e32 v98, v102
	v_permlane16_swap_b32_e32 v99, v103
	v_permlane16_swap_b32_e32 v104, v108
	v_permlane16_swap_b32_e32 v105, v109
	v_permlane16_swap_b32_e32 v106, v110
	v_permlane16_swap_b32_e32 v107, v111
	v_permlane16_swap_b32_e32 v80, v84
	v_permlane16_swap_b32_e32 v81, v85
	v_permlane16_swap_b32_e32 v82, v86
	v_permlane16_swap_b32_e32 v83, v87
	v_permlane16_swap_b32_e32 v88, v92
	v_permlane16_swap_b32_e32 v89, v93
	v_permlane16_swap_b32_e32 v90, v94
	v_permlane16_swap_b32_e32 v91, v95
	v_permlane16_swap_b32_e32 v64, v68
	v_permlane16_swap_b32_e32 v65, v69
	v_permlane16_swap_b32_e32 v66, v70
	v_permlane16_swap_b32_e32 v67, v71
	v_permlane16_swap_b32_e32 v72, v76
	v_permlane16_swap_b32_e32 v73, v77
	v_permlane16_swap_b32_e32 v74, v78
	v_permlane16_swap_b32_e32 v75, v79
	v_permlane16_swap_b32_e32 v48, v52
	v_permlane16_swap_b32_e32 v49, v53
	v_permlane16_swap_b32_e32 v50, v54
	v_permlane16_swap_b32_e32 v51, v55
	v_permlane16_swap_b32_e32 v56, v60
	v_permlane16_swap_b32_e32 v57, v61
	v_permlane16_swap_b32_e32 v58, v62
	v_permlane16_swap_b32_e32 v59, v63
	v_permlane16_swap_b32_e32 v32, v36
	v_permlane16_swap_b32_e32 v33, v37
	v_permlane16_swap_b32_e32 v34, v38
	v_permlane16_swap_b32_e32 v35, v39
	v_permlane16_swap_b32_e32 v40, v44
	v_permlane16_swap_b32_e32 v41, v45
	v_permlane16_swap_b32_e32 v42, v46
	v_permlane16_swap_b32_e32 v43, v47
	v_permlane16_swap_b32_e32 v16, v20
	v_permlane16_swap_b32_e32 v17, v21
	v_permlane16_swap_b32_e32 v18, v22
	v_permlane16_swap_b32_e32 v19, v23
	v_permlane16_swap_b32_e32 v24, v28
	v_permlane16_swap_b32_e32 v25, v29
	v_permlane16_swap_b32_e32 v26, v30
	v_permlane16_swap_b32_e32 v27, v31
	v_permlane16_swap_b32_e32 v0, v4
	v_permlane16_swap_b32_e32 v1, v5
	v_permlane16_swap_b32_e32 v2, v6
	v_permlane16_swap_b32_e32 v3, v7
	v_permlane16_swap_b32_e32 v8, v12
	v_permlane16_swap_b32_e32 v9, v13
	v_permlane16_swap_b32_e32 v10, v14
	v_permlane16_swap_b32_e32 v11, v15
	v_permlane32_swap_b32_e32 v112, v116
	v_permlane32_swap_b32_e32 v113, v117
	v_permlane32_swap_b32_e32 v114, v118
	v_permlane32_swap_b32_e32 v115, v119
	v_permlane32_swap_b32_e32 v120, v124
	v_permlane32_swap_b32_e32 v121, v125
	v_permlane32_swap_b32_e32 v122, v126
	v_permlane32_swap_b32_e32 v123, v127
	v_permlane32_swap_b32_e32 v96, v100
	v_permlane32_swap_b32_e32 v97, v101
	v_permlane32_swap_b32_e32 v98, v102
	v_permlane32_swap_b32_e32 v99, v103
	v_permlane32_swap_b32_e32 v104, v108
	v_permlane32_swap_b32_e32 v105, v109
	v_permlane32_swap_b32_e32 v106, v110
	v_permlane32_swap_b32_e32 v107, v111
	v_permlane32_swap_b32_e32 v80, v84
	v_permlane32_swap_b32_e32 v81, v85
	v_permlane32_swap_b32_e32 v82, v86
	v_permlane32_swap_b32_e32 v83, v87
	v_permlane32_swap_b32_e32 v88, v92
	v_permlane32_swap_b32_e32 v89, v93
	v_permlane32_swap_b32_e32 v90, v94
	v_permlane32_swap_b32_e32 v91, v95
	v_permlane32_swap_b32_e32 v64, v68
	v_permlane32_swap_b32_e32 v65, v69
	v_permlane32_swap_b32_e32 v66, v70
	v_permlane32_swap_b32_e32 v67, v71
	v_permlane32_swap_b32_e32 v72, v76
	v_permlane32_swap_b32_e32 v73, v77
	v_permlane32_swap_b32_e32 v74, v78
	v_permlane32_swap_b32_e32 v75, v79
	v_permlane32_swap_b32_e32 v48, v52
	v_permlane32_swap_b32_e32 v49, v53
	v_permlane32_swap_b32_e32 v50, v54
	v_permlane32_swap_b32_e32 v51, v55
	v_permlane32_swap_b32_e32 v56, v60
	v_permlane32_swap_b32_e32 v57, v61
	v_permlane32_swap_b32_e32 v58, v62
	v_permlane32_swap_b32_e32 v59, v63
	v_permlane32_swap_b32_e32 v32, v36
	v_permlane32_swap_b32_e32 v33, v37
	v_permlane32_swap_b32_e32 v34, v38
	v_permlane32_swap_b32_e32 v35, v39
	v_permlane32_swap_b32_e32 v40, v44
	v_permlane32_swap_b32_e32 v41, v45
	v_permlane32_swap_b32_e32 v42, v46
	v_permlane32_swap_b32_e32 v43, v47
	v_permlane32_swap_b32_e32 v16, v20
	v_permlane32_swap_b32_e32 v17, v21
	v_permlane32_swap_b32_e32 v18, v22
	v_permlane32_swap_b32_e32 v19, v23
	v_permlane32_swap_b32_e32 v24, v28
	v_permlane32_swap_b32_e32 v25, v29
	v_permlane32_swap_b32_e32 v26, v30
	v_permlane32_swap_b32_e32 v27, v31
	v_permlane32_swap_b32_e32 v0, v4
	v_permlane32_swap_b32_e32 v1, v5
	v_permlane32_swap_b32_e32 v2, v6
	v_permlane32_swap_b32_e32 v3, v7
	v_permlane32_swap_b32_e32 v8, v12
	v_permlane32_swap_b32_e32 v9, v13
	v_permlane32_swap_b32_e32 v10, v14
	v_permlane32_swap_b32_e32 v11, v15
	s_nop 1
